# write-through (sc0 sc1) epilogue stores of the residual stream (down/out-projection) and of the gate*up activations so the L2 write-back at the next grid barrier is short
# speedup vs baseline: 1.0096x; 1.0096x over previous
; DI int tid512() { int t = threadIdx.x; asm volatile("" : "+v"(t)); return t; }
; DI unsigned voff256(size_t ld) { const int t = tid512(); return (unsigned)(((size_t)(t >> 3) * ld + (t & 7) * 8) * 2); }
; DI void outproj256(const Params& p, int layer, char* smem) {
;     ...
;   for (int i = 0;; ++i) {
;     const int L = tile_of(i, 32 * 8);
;     if (L < 0) break;
;     int tm, tn; tile_mn(L, 32, 8, tm, tn);
;     f32x16 acc[4][2]; zero_acc256(acc);
;     gemm256((const char*)(Yb + (size_t)(256 + tm * 256) * DM), voff256(DM), (size_t)128 * DM, (const char*)(W + (size_t)(tn * 256) * DM), voff256(DM), (size_t)128 * DM, DM / 64, smem, acc);
;     const int t = tid512(), lane = t & 63, w = t >> 6, wm = w >> 2, wn = w & 3, r = lane & 31, h = lane >> 5;
; #pragma unroll
;     for (int mi = 0; mi < 4; ++mi)
; #pragma unroll
;       for (int ni = 0; ni < 2; ++ni) {
;         const int col = tn * 256 + 64 * wn + 32 * ni + r;
;         const float gg = g1[col];
; #pragma unroll
;         for (int reg = 0; reg < 16; ++reg) {
;           const int row = 256 + tm * 256 + 128 * wm + 32 * mi + (reg & 3) + 8 * (reg >> 2) + 4 * h;
;           const float res = (layer == 0) ? __builtin_nontemporal_load(p.x + (size_t)(row - 256) * DM + col) : X[(size_t)row * DM + col];
;           X[(size_t)row * DM + col] = res + gg * acc[mi][ni][reg];
.LBB0_925:
	s_waitcnt vmcnt(0)
	v_and_b32_e32 v130, 0xdf, v0
	v_or_b32_e32 v130, s4, v130
	v_lshlrev_b32_e32 v130, 2, v130
	global_load_dword v137, v130, s[0:1]
	global_load_dword v138, v130, s[0:1] offset:128
	v_ashrrev_i32_e32 v131, 1, v0
	v_and_b32_e32 v131, 0xffffff80, v131
	v_add_u32_e32 v131, s22, v131
	v_lshrrev_b32_e32 v132, 3, v0
	v_and_or_b32 v131, v132, 4, v131
	v_lshl_add_u32 v133, v131, 13, v130
	v_add_u32_e32 v134, 0x2000, v133
	v_add_u32_e32 v135, 0x4000, v133
	v_add_u32_e32 v136, 0x6000, v133
	s_add_u32 s56, s68, 0xffe00000
	s_addc_u32 s57, s69, -1
	s_cmp_lg_u64 s[34:35], 0
	s_cselect_b32 s52, s90, s56
	s_cselect_b32 s53, s91, s57
	s_mov_b64 s[54:55], s[90:91]
	s_add_i32 s12, s12, 1
	s_add_u32 s56, s52, 0x0
	s_addc_u32 s57, s53, 0
	global_load_dword v193, v133, s[56:57]
	global_load_dword v194, v133, s[56:57] offset:128
	global_load_dword v195, v134, s[56:57]
	global_load_dword v196, v134, s[56:57] offset:128
	global_load_dword v197, v135, s[56:57]
	global_load_dword v198, v135, s[56:57] offset:128
	global_load_dword v199, v136, s[56:57]
	global_load_dword v200, v136, s[56:57] offset:128
	s_add_u32 s56, s52, 0x10000
	s_addc_u32 s57, s53, 0
	global_load_dword v201, v133, s[56:57]
	global_load_dword v202, v133, s[56:57] offset:128
	global_load_dword v203, v134, s[56:57]
	global_load_dword v204, v134, s[56:57] offset:128
	global_load_dword v205, v135, s[56:57]
	global_load_dword v206, v135, s[56:57] offset:128
	global_load_dword v207, v136, s[56:57]
	global_load_dword v208, v136, s[56:57] offset:128
	s_add_u32 s56, s52, 0x20000
	s_addc_u32 s57, s53, 0
	global_load_dword v209, v133, s[56:57]
	global_load_dword v210, v133, s[56:57] offset:128
	global_load_dword v211, v134, s[56:57]
	global_load_dword v212, v134, s[56:57] offset:128
	global_load_dword v213, v135, s[56:57]
	global_load_dword v214, v135, s[56:57] offset:128
	global_load_dword v215, v136, s[56:57]
	global_load_dword v216, v136, s[56:57] offset:128
	s_add_u32 s56, s52, 0x30000
	s_addc_u32 s57, s53, 0
	global_load_dword v217, v133, s[56:57]
	global_load_dword v218, v133, s[56:57] offset:128
	global_load_dword v219, v134, s[56:57]
	global_load_dword v220, v134, s[56:57] offset:128
	global_load_dword v221, v135, s[56:57]
	global_load_dword v222, v135, s[56:57] offset:128
	global_load_dword v223, v136, s[56:57]
	global_load_dword v224, v136, s[56:57] offset:128
	s_waitcnt vmcnt(16)
	v_fmac_f32_e32 v193, v114, v137
	v_fmac_f32_e32 v194, v98, v138
	v_fmac_f32_e32 v195, v115, v137
	v_fmac_f32_e32 v196, v99, v138
	v_fmac_f32_e32 v197, v116, v137
	v_fmac_f32_e32 v198, v100, v138
	v_fmac_f32_e32 v199, v117, v137
	v_fmac_f32_e32 v200, v101, v138
	v_fmac_f32_e32 v201, v118, v137
	v_fmac_f32_e32 v202, v102, v138
	v_fmac_f32_e32 v203, v119, v137
	v_fmac_f32_e32 v204, v103, v138
	v_fmac_f32_e32 v205, v120, v137
	v_fmac_f32_e32 v206, v104, v138
	v_fmac_f32_e32 v207, v121, v137
	v_fmac_f32_e32 v208, v105, v138
	s_add_u32 s56, s52, 0x40000
	s_addc_u32 s57, s53, 0
	global_load_dword v225, v133, s[56:57]
	global_load_dword v226, v133, s[56:57] offset:128
	global_load_dword v227, v134, s[56:57]
	global_load_dword v228, v134, s[56:57] offset:128
	global_load_dword v229, v135, s[56:57]
	global_load_dword v230, v135, s[56:57] offset:128
	global_load_dword v231, v136, s[56:57]
	global_load_dword v237, v136, s[56:57] offset:128
	s_add_u32 s56, s52, 0x50000
	s_addc_u32 s57, s53, 0
	global_load_dword v238, v133, s[56:57]
	global_load_dword v239, v133, s[56:57] offset:128
	global_load_dword v240, v134, s[56:57]
	global_load_dword v241, v134, s[56:57] offset:128
	global_load_dword v242, v135, s[56:57]
	global_load_dword v243, v135, s[56:57] offset:128
	global_load_dword v244, v136, s[56:57]
	global_load_dword v245, v136, s[56:57] offset:128
	s_add_u32 s58, s54, 0x0
	s_addc_u32 s59, s55, 0
	global_store_dword v133, v193, s[58:59] sc0 sc1
	global_store_dword v133, v194, s[58:59] offset:128 sc0 sc1
	global_store_dword v134, v195, s[58:59] sc0 sc1
	global_store_dword v134, v196, s[58:59] offset:128 sc0 sc1
	global_store_dword v135, v197, s[58:59] sc0 sc1
	global_store_dword v135, v198, s[58:59] offset:128 sc0 sc1
	global_store_dword v136, v199, s[58:59] sc0 sc1
	global_store_dword v136, v200, s[58:59] offset:128 sc0 sc1
	s_add_u32 s58, s54, 0x10000
	s_addc_u32 s59, s55, 0
	global_store_dword v133, v201, s[58:59] sc0 sc1
	global_store_dword v133, v202, s[58:59] offset:128 sc0 sc1
	global_store_dword v134, v203, s[58:59] sc0 sc1
	global_store_dword v134, v204, s[58:59] offset:128 sc0 sc1
	global_store_dword v135, v205, s[58:59] sc0 sc1
	global_store_dword v135, v206, s[58:59] offset:128 sc0 sc1
	global_store_dword v136, v207, s[58:59] sc0 sc1
	global_store_dword v136, v208, s[58:59] offset:128 sc0 sc1
	s_waitcnt vmcnt(32)
; DI void outproj256(const Params& p, int layer, char* smem) {
;     ...
; #pragma unroll
;     for (int mi = 0; mi < 4; ++mi)
; #pragma unroll
;       for (int ni = 0; ni < 2; ++ni) {
;         const int col = tn * 256 + 64 * wn + 32 * ni + r;
;         const float gg = g1[col];
; #pragma unroll
;         for (int reg = 0; reg < 16; ++reg) {
;           const int row = 256 + tm * 256 + 128 * wm + 32 * mi + (reg & 3) + 8 * (reg >> 2) + 4 * h;
;           const float res = (layer == 0) ? __builtin_nontemporal_load(p.x + (size_t)(row - 256) * DM + col) : X[(size_t)row * DM + col];
;           X[(size_t)row * DM + col] = res + gg * acc[mi][ni][reg];
;         }
;       }
	v_fmac_f32_e32 v209, v122, v137
	v_fmac_f32_e32 v210, v106, v138
	v_fmac_f32_e32 v211, v123, v137
	v_fmac_f32_e32 v212, v107, v138
	v_fmac_f32_e32 v213, v124, v137
	v_fmac_f32_e32 v214, v108, v138
	v_fmac_f32_e32 v215, v125, v137
	v_fmac_f32_e32 v216, v109, v138
	v_fmac_f32_e32 v217, v126, v137
	v_fmac_f32_e32 v218, v110, v138
	v_fmac_f32_e32 v219, v127, v137
	v_fmac_f32_e32 v220, v111, v138
	v_fmac_f32_e32 v221, v128, v137
	v_fmac_f32_e32 v222, v112, v138
	v_fmac_f32_e32 v223, v129, v137
	v_fmac_f32_e32 v224, v113, v138
	s_add_u32 s56, s52, 0x60000
	s_addc_u32 s57, s53, 0
	global_load_dword v193, v133, s[56:57]
	global_load_dword v194, v133, s[56:57] offset:128
	global_load_dword v195, v134, s[56:57]
	global_load_dword v196, v134, s[56:57] offset:128
	global_load_dword v197, v135, s[56:57]
	global_load_dword v198, v135, s[56:57] offset:128
	global_load_dword v199, v136, s[56:57]
	global_load_dword v200, v136, s[56:57] offset:128
	s_add_u32 s56, s52, 0x70000
	s_addc_u32 s57, s53, 0
	global_load_dword v201, v133, s[56:57]
	global_load_dword v202, v133, s[56:57] offset:128
	global_load_dword v203, v134, s[56:57]
	global_load_dword v204, v134, s[56:57] offset:128
	global_load_dword v205, v135, s[56:57]
	global_load_dword v206, v135, s[56:57] offset:128
	global_load_dword v207, v136, s[56:57]
	global_load_dword v208, v136, s[56:57] offset:128
	s_add_u32 s58, s54, 0x20000
	s_addc_u32 s59, s55, 0
	global_store_dword v133, v209, s[58:59] sc0 sc1
	global_store_dword v133, v210, s[58:59] offset:128 sc0 sc1
	global_store_dword v134, v211, s[58:59] sc0 sc1
	global_store_dword v134, v212, s[58:59] offset:128 sc0 sc1
	global_store_dword v135, v213, s[58:59] sc0 sc1
	global_store_dword v135, v214, s[58:59] offset:128 sc0 sc1
	global_store_dword v136, v215, s[58:59] sc0 sc1
	global_store_dword v136, v216, s[58:59] offset:128 sc0 sc1
	s_add_u32 s58, s54, 0x30000
	s_addc_u32 s59, s55, 0
	global_store_dword v133, v217, s[58:59] sc0 sc1
	global_store_dword v133, v218, s[58:59] offset:128 sc0 sc1
	global_store_dword v134, v219, s[58:59] sc0 sc1
	global_store_dword v134, v220, s[58:59] offset:128 sc0 sc1
	global_store_dword v135, v221, s[58:59] sc0 sc1
	global_store_dword v135, v222, s[58:59] offset:128 sc0 sc1
	global_store_dword v136, v223, s[58:59] sc0 sc1
	global_store_dword v136, v224, s[58:59] offset:128 sc0 sc1
	s_waitcnt vmcnt(48)
	v_fmac_f32_e32 v225, v82, v137
	v_fmac_f32_e32 v226, v66, v138
	v_fmac_f32_e32 v227, v83, v137
	v_fmac_f32_e32 v228, v67, v138
	v_fmac_f32_e32 v229, v84, v137
	v_fmac_f32_e32 v230, v68, v138
	v_fmac_f32_e32 v231, v85, v137
	v_fmac_f32_e32 v237, v69, v138
	v_fmac_f32_e32 v238, v86, v137
	v_fmac_f32_e32 v239, v70, v138
	v_fmac_f32_e32 v240, v87, v137
	v_fmac_f32_e32 v241, v71, v138
	v_fmac_f32_e32 v242, v88, v137
	v_fmac_f32_e32 v243, v72, v138
	v_fmac_f32_e32 v244, v89, v137
	v_fmac_f32_e32 v245, v73, v138
	s_add_u32 s56, s52, 0x80000
	s_addc_u32 s57, s53, 0
	global_load_dword v209, v133, s[56:57]
	global_load_dword v210, v133, s[56:57] offset:128
	global_load_dword v211, v134, s[56:57]
	global_load_dword v212, v134, s[56:57] offset:128
	global_load_dword v213, v135, s[56:57]
	global_load_dword v214, v135, s[56:57] offset:128
	global_load_dword v215, v136, s[56:57]
	global_load_dword v216, v136, s[56:57] offset:128
	s_add_u32 s56, s52, 0x90000
	s_addc_u32 s57, s53, 0
	global_load_dword v217, v133, s[56:57]
	global_load_dword v218, v133, s[56:57] offset:128
	global_load_dword v219, v134, s[56:57]
	global_load_dword v220, v134, s[56:57] offset:128
	global_load_dword v221, v135, s[56:57]
	global_load_dword v222, v135, s[56:57] offset:128
	global_load_dword v223, v136, s[56:57]
	global_load_dword v224, v136, s[56:57] offset:128
	s_add_u32 s58, s54, 0x40000
	s_addc_u32 s59, s55, 0
	global_store_dword v133, v225, s[58:59] sc0 sc1
	global_store_dword v133, v226, s[58:59] offset:128 sc0 sc1
	global_store_dword v134, v227, s[58:59] sc0 sc1
	global_store_dword v134, v228, s[58:59] offset:128 sc0 sc1
	global_store_dword v135, v229, s[58:59] sc0 sc1
	global_store_dword v135, v230, s[58:59] offset:128 sc0 sc1
	global_store_dword v136, v231, s[58:59] sc0 sc1
	global_store_dword v136, v237, s[58:59] offset:128 sc0 sc1
	s_add_u32 s58, s54, 0x50000
	s_addc_u32 s59, s55, 0
	global_store_dword v133, v238, s[58:59] sc0 sc1
	global_store_dword v133, v239, s[58:59] offset:128 sc0 sc1
	global_store_dword v134, v240, s[58:59] sc0 sc1
	global_store_dword v134, v241, s[58:59] offset:128 sc0 sc1
	global_store_dword v135, v242, s[58:59] sc0 sc1
	global_store_dword v135, v243, s[58:59] offset:128 sc0 sc1
	global_store_dword v136, v244, s[58:59] sc0 sc1
	global_store_dword v136, v245, s[58:59] offset:128 sc0 sc1
	s_waitcnt vmcnt(48)
; DI void outproj256(const Params& p, int layer, char* smem) {
;     ...
; #pragma unroll
;     for (int mi = 0; mi < 4; ++mi)
; #pragma unroll
;       for (int ni = 0; ni < 2; ++ni) {
;         const int col = tn * 256 + 64 * wn + 32 * ni + r;
;         const float gg = g1[col];
; #pragma unroll
;         for (int reg = 0; reg < 16; ++reg) {
;           const int row = 256 + tm * 256 + 128 * wm + 32 * mi + (reg & 3) + 8 * (reg >> 2) + 4 * h;
;           const float res = (layer == 0) ? __builtin_nontemporal_load(p.x + (size_t)(row - 256) * DM + col) : X[(size_t)row * DM + col];
;           X[(size_t)row * DM + col] = res + gg * acc[mi][ni][reg];
;         }
;       }
	v_fmac_f32_e32 v193, v90, v137
	v_fmac_f32_e32 v194, v74, v138
	v_fmac_f32_e32 v195, v91, v137
	v_fmac_f32_e32 v196, v75, v138
	v_fmac_f32_e32 v197, v92, v137
	v_fmac_f32_e32 v198, v76, v138
	v_fmac_f32_e32 v199, v93, v137
	v_fmac_f32_e32 v200, v77, v138
	v_fmac_f32_e32 v201, v94, v137
	v_fmac_f32_e32 v202, v78, v138
	v_fmac_f32_e32 v203, v95, v137
	v_fmac_f32_e32 v204, v79, v138
	v_fmac_f32_e32 v205, v96, v137
	v_fmac_f32_e32 v206, v80, v138
	v_fmac_f32_e32 v207, v97, v137
	v_fmac_f32_e32 v208, v81, v138
	s_add_u32 s56, s52, 0xa0000
	s_addc_u32 s57, s53, 0
	global_load_dword v225, v133, s[56:57]
	global_load_dword v226, v133, s[56:57] offset:128
	global_load_dword v227, v134, s[56:57]
	global_load_dword v228, v134, s[56:57] offset:128
	global_load_dword v229, v135, s[56:57]
	global_load_dword v230, v135, s[56:57] offset:128
	global_load_dword v231, v136, s[56:57]
	global_load_dword v237, v136, s[56:57] offset:128
	s_add_u32 s56, s52, 0xb0000
	s_addc_u32 s57, s53, 0
	global_load_dword v238, v133, s[56:57]
	global_load_dword v239, v133, s[56:57] offset:128
	global_load_dword v240, v134, s[56:57]
	global_load_dword v241, v134, s[56:57] offset:128
	global_load_dword v242, v135, s[56:57]
	global_load_dword v243, v135, s[56:57] offset:128
	global_load_dword v244, v136, s[56:57]
	global_load_dword v245, v136, s[56:57] offset:128
	s_add_u32 s58, s54, 0x60000
	s_addc_u32 s59, s55, 0
	global_store_dword v133, v193, s[58:59] sc0 sc1
	global_store_dword v133, v194, s[58:59] offset:128 sc0 sc1
	global_store_dword v134, v195, s[58:59] sc0 sc1
	global_store_dword v134, v196, s[58:59] offset:128 sc0 sc1
	global_store_dword v135, v197, s[58:59] sc0 sc1
	global_store_dword v135, v198, s[58:59] offset:128 sc0 sc1
	global_store_dword v136, v199, s[58:59] sc0 sc1
	global_store_dword v136, v200, s[58:59] offset:128 sc0 sc1
	s_add_u32 s58, s54, 0x70000
	s_addc_u32 s59, s55, 0
	global_store_dword v133, v201, s[58:59] sc0 sc1
	global_store_dword v133, v202, s[58:59] offset:128 sc0 sc1
	global_store_dword v134, v203, s[58:59] sc0 sc1
	global_store_dword v134, v204, s[58:59] offset:128 sc0 sc1
	global_store_dword v135, v205, s[58:59] sc0 sc1
	global_store_dword v135, v206, s[58:59] offset:128 sc0 sc1
	global_store_dword v136, v207, s[58:59] sc0 sc1
	global_store_dword v136, v208, s[58:59] offset:128 sc0 sc1
	s_waitcnt vmcnt(48)
	v_fmac_f32_e32 v209, v50, v137
	v_fmac_f32_e32 v210, v34, v138
	v_fmac_f32_e32 v211, v51, v137
	v_fmac_f32_e32 v212, v35, v138
	v_fmac_f32_e32 v213, v52, v137
	v_fmac_f32_e32 v214, v36, v138
	v_fmac_f32_e32 v215, v53, v137
	v_fmac_f32_e32 v216, v37, v138
	v_fmac_f32_e32 v217, v54, v137
	v_fmac_f32_e32 v218, v38, v138
	v_fmac_f32_e32 v219, v55, v137
	v_fmac_f32_e32 v220, v39, v138
	v_fmac_f32_e32 v221, v56, v137
	v_fmac_f32_e32 v222, v40, v138
	v_fmac_f32_e32 v223, v57, v137
	v_fmac_f32_e32 v224, v41, v138
	s_add_u32 s56, s52, 0xc0000
	s_addc_u32 s57, s53, 0
	global_load_dword v193, v133, s[56:57]
	global_load_dword v194, v133, s[56:57] offset:128
	global_load_dword v195, v134, s[56:57]
	global_load_dword v196, v134, s[56:57] offset:128
	global_load_dword v197, v135, s[56:57]
	global_load_dword v198, v135, s[56:57] offset:128
	global_load_dword v199, v136, s[56:57]
	global_load_dword v200, v136, s[56:57] offset:128
	s_add_u32 s56, s52, 0xd0000
	s_addc_u32 s57, s53, 0
	global_load_dword v201, v133, s[56:57]
	global_load_dword v202, v133, s[56:57] offset:128
	global_load_dword v203, v134, s[56:57]
	global_load_dword v204, v134, s[56:57] offset:128
	global_load_dword v205, v135, s[56:57]
	global_load_dword v206, v135, s[56:57] offset:128
	global_load_dword v207, v136, s[56:57]
	global_load_dword v208, v136, s[56:57] offset:128
	s_add_u32 s58, s54, 0x80000
	s_addc_u32 s59, s55, 0
	global_store_dword v133, v209, s[58:59] sc0 sc1
	global_store_dword v133, v210, s[58:59] offset:128 sc0 sc1
	global_store_dword v134, v211, s[58:59] sc0 sc1
	global_store_dword v134, v212, s[58:59] offset:128 sc0 sc1
	global_store_dword v135, v213, s[58:59] sc0 sc1
	global_store_dword v135, v214, s[58:59] offset:128 sc0 sc1
	global_store_dword v136, v215, s[58:59] sc0 sc1
	global_store_dword v136, v216, s[58:59] offset:128 sc0 sc1
	s_add_u32 s58, s54, 0x90000
	s_addc_u32 s59, s55, 0
	global_store_dword v133, v217, s[58:59] sc0 sc1
	global_store_dword v133, v218, s[58:59] offset:128 sc0 sc1
	global_store_dword v134, v219, s[58:59] sc0 sc1
	global_store_dword v134, v220, s[58:59] offset:128 sc0 sc1
	global_store_dword v135, v221, s[58:59] sc0 sc1
	global_store_dword v135, v222, s[58:59] offset:128 sc0 sc1
	global_store_dword v136, v223, s[58:59] sc0 sc1
	global_store_dword v136, v224, s[58:59] offset:128 sc0 sc1
	s_waitcnt vmcnt(48)
; DI void outproj256(const Params& p, int layer, char* smem) {
;     ...
; #pragma unroll
;     for (int mi = 0; mi < 4; ++mi)
; #pragma unroll
;       for (int ni = 0; ni < 2; ++ni) {
;         const int col = tn * 256 + 64 * wn + 32 * ni + r;
;         const float gg = g1[col];
; #pragma unroll
;         for (int reg = 0; reg < 16; ++reg) {
;           const int row = 256 + tm * 256 + 128 * wm + 32 * mi + (reg & 3) + 8 * (reg >> 2) + 4 * h;
;           const float res = (layer == 0) ? __builtin_nontemporal_load(p.x + (size_t)(row - 256) * DM + col) : X[(size_t)row * DM + col];
;           X[(size_t)row * DM + col] = res + gg * acc[mi][ni][reg];
;         }
;       }
	v_fmac_f32_e32 v225, v58, v137
	v_fmac_f32_e32 v226, v42, v138
	v_fmac_f32_e32 v227, v59, v137
	v_fmac_f32_e32 v228, v43, v138
	v_fmac_f32_e32 v229, v60, v137
	v_fmac_f32_e32 v230, v44, v138
	v_fmac_f32_e32 v231, v61, v137
	v_fmac_f32_e32 v237, v45, v138
	v_fmac_f32_e32 v238, v62, v137
	v_fmac_f32_e32 v239, v46, v138
	v_fmac_f32_e32 v240, v63, v137
	v_fmac_f32_e32 v241, v47, v138
	v_fmac_f32_e32 v242, v64, v137
	v_fmac_f32_e32 v243, v48, v138
	v_fmac_f32_e32 v244, v65, v137
	v_fmac_f32_e32 v245, v49, v138
	s_add_u32 s56, s52, 0xe0000
	s_addc_u32 s57, s53, 0
	global_load_dword v209, v133, s[56:57]
	global_load_dword v210, v133, s[56:57] offset:128
	global_load_dword v211, v134, s[56:57]
	global_load_dword v212, v134, s[56:57] offset:128
	global_load_dword v213, v135, s[56:57]
	global_load_dword v214, v135, s[56:57] offset:128
	global_load_dword v215, v136, s[56:57]
	global_load_dword v216, v136, s[56:57] offset:128
	s_add_u32 s56, s52, 0xf0000
	s_addc_u32 s57, s53, 0
	global_load_dword v217, v133, s[56:57]
	global_load_dword v218, v133, s[56:57] offset:128
	global_load_dword v219, v134, s[56:57]
	global_load_dword v220, v134, s[56:57] offset:128
	global_load_dword v221, v135, s[56:57]
	global_load_dword v222, v135, s[56:57] offset:128
	global_load_dword v223, v136, s[56:57]
	global_load_dword v224, v136, s[56:57] offset:128
	s_add_u32 s58, s54, 0xa0000
	s_addc_u32 s59, s55, 0
	global_store_dword v133, v225, s[58:59] sc0 sc1
	global_store_dword v133, v226, s[58:59] offset:128 sc0 sc1
	global_store_dword v134, v227, s[58:59] sc0 sc1
	global_store_dword v134, v228, s[58:59] offset:128 sc0 sc1
	global_store_dword v135, v229, s[58:59] sc0 sc1
	global_store_dword v135, v230, s[58:59] offset:128 sc0 sc1
	global_store_dword v136, v231, s[58:59] sc0 sc1
	global_store_dword v136, v237, s[58:59] offset:128 sc0 sc1
	s_add_u32 s58, s54, 0xb0000
	s_addc_u32 s59, s55, 0
	global_store_dword v133, v238, s[58:59] sc0 sc1
	global_store_dword v133, v239, s[58:59] offset:128 sc0 sc1
	global_store_dword v134, v240, s[58:59] sc0 sc1
	global_store_dword v134, v241, s[58:59] offset:128 sc0 sc1
	global_store_dword v135, v242, s[58:59] sc0 sc1
	global_store_dword v135, v243, s[58:59] offset:128 sc0 sc1
	global_store_dword v136, v244, s[58:59] sc0 sc1
	global_store_dword v136, v245, s[58:59] offset:128 sc0 sc1
	s_waitcnt vmcnt(48)
	v_fmac_f32_e32 v193, v18, v137
	v_fmac_f32_e32 v194, v2, v138
	v_fmac_f32_e32 v195, v19, v137
	v_fmac_f32_e32 v196, v3, v138
	v_fmac_f32_e32 v197, v20, v137
	v_fmac_f32_e32 v198, v4, v138
	v_fmac_f32_e32 v199, v21, v137
	v_fmac_f32_e32 v200, v5, v138
	v_fmac_f32_e32 v201, v22, v137
	v_fmac_f32_e32 v202, v6, v138
	v_fmac_f32_e32 v203, v23, v137
	v_fmac_f32_e32 v204, v7, v138
	v_fmac_f32_e32 v205, v24, v137
	v_fmac_f32_e32 v206, v8, v138
	v_fmac_f32_e32 v207, v25, v137
	v_fmac_f32_e32 v208, v9, v138
	s_add_u32 s58, s54, 0xc0000
	s_addc_u32 s59, s55, 0
	global_store_dword v133, v193, s[58:59] sc0 sc1
	global_store_dword v133, v194, s[58:59] offset:128 sc0 sc1
	global_store_dword v134, v195, s[58:59] sc0 sc1
	global_store_dword v134, v196, s[58:59] offset:128 sc0 sc1
	global_store_dword v135, v197, s[58:59] sc0 sc1
	global_store_dword v135, v198, s[58:59] offset:128 sc0 sc1
	global_store_dword v136, v199, s[58:59] sc0 sc1
	global_store_dword v136, v200, s[58:59] offset:128 sc0 sc1
	s_add_u32 s58, s54, 0xd0000
	s_addc_u32 s59, s55, 0
	global_store_dword v133, v201, s[58:59] sc0 sc1
	global_store_dword v133, v202, s[58:59] offset:128 sc0 sc1
	global_store_dword v134, v203, s[58:59] sc0 sc1
	global_store_dword v134, v204, s[58:59] offset:128 sc0 sc1
	global_store_dword v135, v205, s[58:59] sc0 sc1
	global_store_dword v135, v206, s[58:59] offset:128 sc0 sc1
	global_store_dword v136, v207, s[58:59] sc0 sc1
	global_store_dword v136, v208, s[58:59] offset:128 sc0 sc1
	s_waitcnt vmcnt(32)
	v_fmac_f32_e32 v209, v26, v137
	v_fmac_f32_e32 v210, v10, v138
	v_fmac_f32_e32 v211, v27, v137
	v_fmac_f32_e32 v212, v11, v138
	v_fmac_f32_e32 v213, v28, v137
	v_fmac_f32_e32 v214, v12, v138
	v_fmac_f32_e32 v215, v29, v137
	v_fmac_f32_e32 v216, v13, v138
	v_fmac_f32_e32 v217, v30, v137
	v_fmac_f32_e32 v218, v14, v138
	v_fmac_f32_e32 v219, v31, v137
	v_fmac_f32_e32 v220, v15, v138
	v_fmac_f32_e32 v221, v32, v137
	v_fmac_f32_e32 v222, v16, v138
	v_fmac_f32_e32 v223, v33, v137
	v_fmac_f32_e32 v224, v17, v138
	s_add_u32 s58, s54, 0xe0000
	s_addc_u32 s59, s55, 0
	global_store_dword v133, v209, s[58:59] sc0 sc1
	global_store_dword v133, v210, s[58:59] offset:128 sc0 sc1
	global_store_dword v134, v211, s[58:59] sc0 sc1
	global_store_dword v134, v212, s[58:59] offset:128 sc0 sc1
	global_store_dword v135, v213, s[58:59] sc0 sc1
	global_store_dword v135, v214, s[58:59] offset:128 sc0 sc1
	global_store_dword v136, v215, s[58:59] sc0 sc1
	global_store_dword v136, v216, s[58:59] offset:128 sc0 sc1
	s_add_u32 s58, s54, 0xf0000
	s_addc_u32 s59, s55, 0
	global_store_dword v133, v217, s[58:59] sc0 sc1
	global_store_dword v133, v218, s[58:59] offset:128 sc0 sc1
	global_store_dword v134, v219, s[58:59] sc0 sc1
	global_store_dword v134, v220, s[58:59] offset:128 sc0 sc1
	global_store_dword v135, v221, s[58:59] sc0 sc1
	global_store_dword v135, v222, s[58:59] offset:128 sc0 sc1
	global_store_dword v136, v223, s[58:59] sc0 sc1
	global_store_dword v136, v224, s[58:59] offset:128 sc0 sc1
	s_branch .LBB0_915

; DI float silu(float x) { return x * __builtin_amdgcn_rcpf(1.f + __expf(-x)); }
; DI void gateup256(const Params& p, int layer, char* smem) {
;     ...
; #pragma unroll
;     for (int mi = 0; mi < 4; ++mi)
; #pragma unroll
;       for (int reg = 0; reg < 16; ++reg) {
;         const int row = 256 + tm * 256 + 128 * wm + 32 * mi + (reg & 3) + 8 * (reg >> 2) + 4 * h;
;         const int col = nb * 128 + 32 * wn + r;
;         HID[(size_t)row * DFF + col] = f2bf(silu(acc[mi][0][reg]) * acc[mi][1][reg]);
;       }
.LBB0_1568:
	s_waitcnt vmcnt(1)
	v_ashrrev_i32_e32 v131, 1, v193
	v_and_b32_e32 v131, 0xffffff80, v131
	v_add_u32_e32 v132, s4, v131
	v_lshrrev_b32_e32 v133, 3, v193
	v_and_or_b32 v132, v133, 4, v132
	v_mul_f32_e32 v133, 0xbfb8aa3b, v114
	v_exp_f32_e32 v133, v133
	v_lshrrev_b32_e32 v131, 1, v193
	v_and_b32_e32 v130, 31, v193
	v_and_b32_e32 v131, 0x60, v131
	v_add_f32_e32 v133, 1.0, v133
	v_rcp_f32_e32 v133, v133
	v_or3_b32 v130, v130, v131, s6
	v_readlane_b32 s4, v254, 34
	v_ashrrev_i32_e32 v131, 31, v130
	v_mul_f32_e32 v114, v114, v133
	v_mul_f32_e32 v98, v98, v114
	v_mul_f32_e32 v114, 0xbfb8aa3b, v115
	v_exp_f32_e32 v114, v114
	v_readlane_b32 s5, v254, 35
	v_cvt_pk_bf16_f32 v98, v98, s0
	s_add_i32 s14, s14, 1
	v_add_f32_e32 v114, 1.0, v114
	v_rcp_f32_e32 v114, v114
	v_lshl_add_u64 v[130:131], v[130:131], 1, s[4:5]
	s_waitcnt vmcnt(0)
	v_mad_i64_i32 v[134:135], s[4:5], v132, s39, v[130:131]
	v_mul_f32_e32 v114, v115, v114
	global_store_short v[134:135], v98, off sc0 sc1
	v_or_b32_e32 v98, 1, v132
	v_mul_f32_e32 v99, v99, v114
	v_cvt_pk_bf16_f32 v114, v99, s0
	v_mad_i64_i32 v[98:99], s[4:5], v98, s39, v[130:131]
	global_store_short v[98:99], v114, off sc0 sc1
	v_mul_f32_e32 v99, 0xbfb8aa3b, v116
	v_exp_f32_e32 v99, v99
	v_or_b32_e32 v98, 2, v132
	v_add_f32_e32 v99, 1.0, v99
	v_rcp_f32_e32 v99, v99
	s_nop 0
	v_mul_f32_e32 v99, v116, v99
	v_mul_f32_e32 v99, v100, v99
	v_cvt_pk_bf16_f32 v100, v99, s0
	v_mad_i64_i32 v[98:99], s[4:5], v98, s39, v[130:131]
	global_store_short v[98:99], v100, off sc0 sc1
	v_mul_f32_e32 v99, 0xbfb8aa3b, v117
	v_exp_f32_e32 v99, v99
	v_or_b32_e32 v98, 3, v132
	v_add_f32_e32 v99, 1.0, v99
	v_rcp_f32_e32 v99, v99
	s_nop 0
	v_mul_f32_e32 v99, v117, v99
	v_mul_f32_e32 v99, v101, v99
	v_cvt_pk_bf16_f32 v100, v99, s0
	v_mad_i64_i32 v[98:99], s[4:5], v98, s39, v[130:131]
	global_store_short v[98:99], v100, off sc0 sc1
	v_mul_f32_e32 v99, 0xbfb8aa3b, v118
	v_exp_f32_e32 v99, v99
	v_or_b32_e32 v98, 8, v132
	v_add_f32_e32 v99, 1.0, v99
	v_rcp_f32_e32 v99, v99
	s_nop 0
	v_mul_f32_e32 v99, v118, v99
	v_mul_f32_e32 v99, v102, v99
	v_cvt_pk_bf16_f32 v100, v99, s0
	v_mad_i64_i32 v[98:99], s[4:5], v98, s39, v[130:131]
	global_store_short v[98:99], v100, off sc0 sc1
	v_mul_f32_e32 v99, 0xbfb8aa3b, v119
	v_exp_f32_e32 v99, v99
	v_or_b32_e32 v98, 9, v132
	v_add_f32_e32 v99, 1.0, v99
	v_rcp_f32_e32 v99, v99
	s_nop 0
	v_mul_f32_e32 v99, v119, v99
	v_mul_f32_e32 v99, v103, v99
	v_cvt_pk_bf16_f32 v100, v99, s0
	v_mad_i64_i32 v[98:99], s[4:5], v98, s39, v[130:131]
	global_store_short v[98:99], v100, off sc0 sc1
	v_mul_f32_e32 v99, 0xbfb8aa3b, v120
	v_exp_f32_e32 v99, v99
	v_or_b32_e32 v98, 10, v132
	v_add_f32_e32 v99, 1.0, v99
	v_rcp_f32_e32 v99, v99
	s_nop 0
	v_mul_f32_e32 v99, v120, v99
	v_mul_f32_e32 v99, v104, v99
	v_cvt_pk_bf16_f32 v100, v99, s0
	v_mad_i64_i32 v[98:99], s[4:5], v98, s39, v[130:131]
	global_store_short v[98:99], v100, off sc0 sc1
	v_mul_f32_e32 v99, 0xbfb8aa3b, v121
	v_exp_f32_e32 v99, v99
	v_or_b32_e32 v98, 11, v132
	v_add_f32_e32 v99, 1.0, v99
	v_rcp_f32_e32 v99, v99
	s_nop 0
	v_mul_f32_e32 v99, v121, v99
	v_mul_f32_e32 v99, v105, v99
	v_cvt_pk_bf16_f32 v100, v99, s0
	v_mad_i64_i32 v[98:99], s[4:5], v98, s39, v[130:131]
	global_store_short v[98:99], v100, off sc0 sc1
	v_mul_f32_e32 v99, 0xbfb8aa3b, v122
	v_exp_f32_e32 v99, v99
	v_or_b32_e32 v98, 16, v132
	v_add_f32_e32 v99, 1.0, v99
	v_rcp_f32_e32 v99, v99
	s_nop 0
	v_mul_f32_e32 v99, v122, v99
	v_mul_f32_e32 v99, v106, v99
	v_cvt_pk_bf16_f32 v100, v99, s0
	v_mad_i64_i32 v[98:99], s[4:5], v98, s39, v[130:131]
	global_store_short v[98:99], v100, off sc0 sc1
	v_mul_f32_e32 v99, 0xbfb8aa3b, v123
	v_exp_f32_e32 v99, v99
	v_or_b32_e32 v98, 17, v132
	v_add_f32_e32 v99, 1.0, v99
	v_rcp_f32_e32 v99, v99
	s_nop 0
	v_mul_f32_e32 v99, v123, v99
	v_mul_f32_e32 v99, v107, v99
	v_cvt_pk_bf16_f32 v100, v99, s0
	v_mad_i64_i32 v[98:99], s[4:5], v98, s39, v[130:131]
	global_store_short v[98:99], v100, off sc0 sc1
	v_mul_f32_e32 v99, 0xbfb8aa3b, v124
	v_exp_f32_e32 v99, v99
	v_or_b32_e32 v98, 18, v132
	v_add_f32_e32 v99, 1.0, v99
	v_rcp_f32_e32 v99, v99
	s_nop 0
	v_mul_f32_e32 v99, v124, v99
	v_mul_f32_e32 v99, v108, v99
	v_cvt_pk_bf16_f32 v100, v99, s0
	v_mad_i64_i32 v[98:99], s[4:5], v98, s39, v[130:131]
	global_store_short v[98:99], v100, off sc0 sc1
	v_mul_f32_e32 v99, 0xbfb8aa3b, v125
	v_exp_f32_e32 v99, v99
	v_or_b32_e32 v98, 19, v132
	v_add_f32_e32 v99, 1.0, v99
	v_rcp_f32_e32 v99, v99
	s_nop 0
	v_mul_f32_e32 v99, v125, v99
	v_mul_f32_e32 v99, v109, v99
	v_cvt_pk_bf16_f32 v100, v99, s0
	v_mad_i64_i32 v[98:99], s[4:5], v98, s39, v[130:131]
	global_store_short v[98:99], v100, off sc0 sc1
	v_mul_f32_e32 v99, 0xbfb8aa3b, v126
	v_exp_f32_e32 v99, v99
	v_or_b32_e32 v98, 24, v132
	v_add_f32_e32 v99, 1.0, v99
	v_rcp_f32_e32 v99, v99
	s_nop 0
	v_mul_f32_e32 v99, v126, v99
	v_mul_f32_e32 v99, v110, v99
	v_cvt_pk_bf16_f32 v100, v99, s0
	v_mad_i64_i32 v[98:99], s[4:5], v98, s39, v[130:131]
	global_store_short v[98:99], v100, off sc0 sc1
	v_mul_f32_e32 v99, 0xbfb8aa3b, v127
	v_exp_f32_e32 v99, v99
	v_or_b32_e32 v98, 25, v132
	v_add_f32_e32 v99, 1.0, v99
	v_rcp_f32_e32 v99, v99
	s_nop 0
	v_mul_f32_e32 v99, v127, v99
	v_mul_f32_e32 v99, v111, v99
	v_cvt_pk_bf16_f32 v100, v99, s0
	v_mad_i64_i32 v[98:99], s[4:5], v98, s39, v[130:131]
	global_store_short v[98:99], v100, off sc0 sc1
	v_mul_f32_e32 v99, 0xbfb8aa3b, v128
	v_exp_f32_e32 v99, v99
	v_or_b32_e32 v98, 26, v132
	v_add_f32_e32 v99, 1.0, v99
	v_rcp_f32_e32 v99, v99
	s_nop 0
	v_mul_f32_e32 v99, v128, v99
	v_mul_f32_e32 v99, v112, v99
	v_cvt_pk_bf16_f32 v100, v99, s0
	v_mad_i64_i32 v[98:99], s[4:5], v98, s39, v[130:131]
; DI float silu(float x) { return x * __builtin_amdgcn_rcpf(1.f + __expf(-x)); }
; DI void gateup256(const Params& p, int layer, char* smem) {
;     ...
; #pragma unroll
;     for (int mi = 0; mi < 4; ++mi)
; #pragma unroll
;       for (int reg = 0; reg < 16; ++reg) {
;         const int row = 256 + tm * 256 + 128 * wm + 32 * mi + (reg & 3) + 8 * (reg >> 2) + 4 * h;
;         const int col = nb * 128 + 32 * wn + r;
;         HID[(size_t)row * DFF + col] = f2bf(silu(acc[mi][0][reg]) * acc[mi][1][reg]);
;       }
	global_store_short v[98:99], v100, off sc0 sc1
	v_mul_f32_e32 v99, 0xbfb8aa3b, v129
	v_exp_f32_e32 v99, v99
	v_or_b32_e32 v98, 27, v132
	v_add_f32_e32 v99, 1.0, v99
	v_rcp_f32_e32 v99, v99
	s_nop 0
	v_mul_f32_e32 v99, v129, v99
	v_mul_f32_e32 v99, v113, v99
	v_cvt_pk_bf16_f32 v100, v99, s0
	v_mad_i64_i32 v[98:99], s[4:5], v98, s39, v[130:131]
	global_store_short v[98:99], v100, off sc0 sc1
	v_mul_f32_e32 v99, 0xbfb8aa3b, v82
	v_exp_f32_e32 v99, v99
	v_or_b32_e32 v98, 32, v132
	v_add_f32_e32 v99, 1.0, v99
	v_rcp_f32_e32 v99, v99
	s_nop 0
	v_mul_f32_e32 v82, v82, v99
	v_mul_f32_e32 v66, v66, v82
	v_mul_f32_e32 v82, 0xbfb8aa3b, v83
	v_exp_f32_e32 v82, v82
	v_cvt_pk_bf16_f32 v66, v66, s0
	v_mad_i64_i32 v[98:99], s[4:5], v98, s39, v[130:131]
	v_add_f32_e32 v82, 1.0, v82
	v_rcp_f32_e32 v82, v82
	global_store_short v[98:99], v66, off sc0 sc1
	v_or_b32_e32 v66, 33, v132
	v_mul_f32_e32 v82, v83, v82
	v_mul_f32_e32 v67, v67, v82
	v_cvt_pk_bf16_f32 v82, v67, s0
	v_mad_i64_i32 v[66:67], s[4:5], v66, s39, v[130:131]
	global_store_short v[66:67], v82, off sc0 sc1
	v_mul_f32_e32 v67, 0xbfb8aa3b, v84
	v_exp_f32_e32 v67, v67
	v_or_b32_e32 v66, 34, v132
	v_add_f32_e32 v67, 1.0, v67
	v_rcp_f32_e32 v67, v67
	s_nop 0
	v_mul_f32_e32 v67, v84, v67
	v_mul_f32_e32 v67, v68, v67
	v_cvt_pk_bf16_f32 v68, v67, s0
	v_mad_i64_i32 v[66:67], s[4:5], v66, s39, v[130:131]
	global_store_short v[66:67], v68, off sc0 sc1
	v_mul_f32_e32 v67, 0xbfb8aa3b, v85
	v_exp_f32_e32 v67, v67
	v_or_b32_e32 v66, 35, v132
	v_add_f32_e32 v67, 1.0, v67
	v_rcp_f32_e32 v67, v67
	s_nop 0
	v_mul_f32_e32 v67, v85, v67
	v_mul_f32_e32 v67, v69, v67
	v_cvt_pk_bf16_f32 v68, v67, s0
	v_mad_i64_i32 v[66:67], s[4:5], v66, s39, v[130:131]
	global_store_short v[66:67], v68, off sc0 sc1
	v_mul_f32_e32 v67, 0xbfb8aa3b, v86
	v_exp_f32_e32 v67, v67
	v_or_b32_e32 v66, 40, v132
	v_add_f32_e32 v67, 1.0, v67
	v_rcp_f32_e32 v67, v67
	s_nop 0
	v_mul_f32_e32 v67, v86, v67
	v_mul_f32_e32 v67, v70, v67
	v_cvt_pk_bf16_f32 v68, v67, s0
	v_mad_i64_i32 v[66:67], s[4:5], v66, s39, v[130:131]
	global_store_short v[66:67], v68, off sc0 sc1
	v_mul_f32_e32 v67, 0xbfb8aa3b, v87
	v_exp_f32_e32 v67, v67
	v_or_b32_e32 v66, 41, v132
	v_add_f32_e32 v67, 1.0, v67
	v_rcp_f32_e32 v67, v67
	s_nop 0
	v_mul_f32_e32 v67, v87, v67
	v_mul_f32_e32 v67, v71, v67
	v_cvt_pk_bf16_f32 v68, v67, s0
	v_mad_i64_i32 v[66:67], s[4:5], v66, s39, v[130:131]
	global_store_short v[66:67], v68, off sc0 sc1
	v_mul_f32_e32 v67, 0xbfb8aa3b, v88
	v_exp_f32_e32 v67, v67
	v_or_b32_e32 v66, 42, v132
	v_add_f32_e32 v67, 1.0, v67
	v_rcp_f32_e32 v67, v67
	s_nop 0
	v_mul_f32_e32 v67, v88, v67
	v_mul_f32_e32 v67, v72, v67
	v_cvt_pk_bf16_f32 v68, v67, s0
	v_mad_i64_i32 v[66:67], s[4:5], v66, s39, v[130:131]
	global_store_short v[66:67], v68, off sc0 sc1
	v_mul_f32_e32 v67, 0xbfb8aa3b, v89
	v_exp_f32_e32 v67, v67
	v_or_b32_e32 v66, 43, v132
	v_add_f32_e32 v67, 1.0, v67
	v_rcp_f32_e32 v67, v67
	s_nop 0
	v_mul_f32_e32 v67, v89, v67
	v_mul_f32_e32 v67, v73, v67
	v_cvt_pk_bf16_f32 v68, v67, s0
	v_mad_i64_i32 v[66:67], s[4:5], v66, s39, v[130:131]
	global_store_short v[66:67], v68, off sc0 sc1
	v_mul_f32_e32 v67, 0xbfb8aa3b, v90
	v_exp_f32_e32 v67, v67
	v_or_b32_e32 v66, 48, v132
	v_add_f32_e32 v67, 1.0, v67
	v_rcp_f32_e32 v67, v67
	s_nop 0
	v_mul_f32_e32 v67, v90, v67
	v_mul_f32_e32 v67, v74, v67
	v_cvt_pk_bf16_f32 v68, v67, s0
	v_mad_i64_i32 v[66:67], s[4:5], v66, s39, v[130:131]
	global_store_short v[66:67], v68, off sc0 sc1
	v_mul_f32_e32 v67, 0xbfb8aa3b, v91
	v_exp_f32_e32 v67, v67
	v_or_b32_e32 v66, 49, v132
	v_add_f32_e32 v67, 1.0, v67
	v_rcp_f32_e32 v67, v67
	s_nop 0
	v_mul_f32_e32 v67, v91, v67
	v_mul_f32_e32 v67, v75, v67
	v_cvt_pk_bf16_f32 v68, v67, s0
	v_mad_i64_i32 v[66:67], s[4:5], v66, s39, v[130:131]
	global_store_short v[66:67], v68, off sc0 sc1
	v_mul_f32_e32 v67, 0xbfb8aa3b, v92
	v_exp_f32_e32 v67, v67
	v_or_b32_e32 v66, 50, v132
	v_add_f32_e32 v67, 1.0, v67
	v_rcp_f32_e32 v67, v67
	s_nop 0
	v_mul_f32_e32 v67, v92, v67
	v_mul_f32_e32 v67, v76, v67
	v_cvt_pk_bf16_f32 v68, v67, s0
	v_mad_i64_i32 v[66:67], s[4:5], v66, s39, v[130:131]
	global_store_short v[66:67], v68, off sc0 sc1
	v_mul_f32_e32 v67, 0xbfb8aa3b, v93
	v_exp_f32_e32 v67, v67
	v_or_b32_e32 v66, 51, v132
	v_add_f32_e32 v67, 1.0, v67
	v_rcp_f32_e32 v67, v67
	s_nop 0
	v_mul_f32_e32 v67, v93, v67
	v_mul_f32_e32 v67, v77, v67
	v_cvt_pk_bf16_f32 v68, v67, s0
	v_mad_i64_i32 v[66:67], s[4:5], v66, s39, v[130:131]
	global_store_short v[66:67], v68, off sc0 sc1
	v_mul_f32_e32 v67, 0xbfb8aa3b, v94
	v_exp_f32_e32 v67, v67
	v_or_b32_e32 v66, 56, v132
	v_add_f32_e32 v67, 1.0, v67
	v_rcp_f32_e32 v67, v67
	s_nop 0
	v_mul_f32_e32 v67, v94, v67
	v_mul_f32_e32 v67, v78, v67
	v_cvt_pk_bf16_f32 v68, v67, s0
	v_mad_i64_i32 v[66:67], s[4:5], v66, s39, v[130:131]
	global_store_short v[66:67], v68, off sc0 sc1
	v_mul_f32_e32 v67, 0xbfb8aa3b, v95
	v_exp_f32_e32 v67, v67
	v_or_b32_e32 v66, 57, v132
	v_add_f32_e32 v67, 1.0, v67
	v_rcp_f32_e32 v67, v67
	s_nop 0
	v_mul_f32_e32 v67, v95, v67
	v_mul_f32_e32 v67, v79, v67
	v_cvt_pk_bf16_f32 v68, v67, s0
	v_mad_i64_i32 v[66:67], s[4:5], v66, s39, v[130:131]
	global_store_short v[66:67], v68, off sc0 sc1
	v_mul_f32_e32 v67, 0xbfb8aa3b, v96
	v_exp_f32_e32 v67, v67
	v_or_b32_e32 v66, 58, v132
	v_add_f32_e32 v67, 1.0, v67
	v_rcp_f32_e32 v67, v67
	s_nop 0
	v_mul_f32_e32 v67, v96, v67
	v_mul_f32_e32 v67, v80, v67
	v_cvt_pk_bf16_f32 v68, v67, s0
	v_mad_i64_i32 v[66:67], s[4:5], v66, s39, v[130:131]
	global_store_short v[66:67], v68, off sc0 sc1
	v_mul_f32_e32 v67, 0xbfb8aa3b, v97
	v_exp_f32_e32 v67, v67
	v_or_b32_e32 v66, 59, v132
	v_add_f32_e32 v67, 1.0, v67
	v_rcp_f32_e32 v67, v67
; DI float silu(float x) { return x * __builtin_amdgcn_rcpf(1.f + __expf(-x)); }
; DI void gateup256(const Params& p, int layer, char* smem) {
;     ...
; #pragma unroll
;     for (int mi = 0; mi < 4; ++mi)
; #pragma unroll
;       for (int reg = 0; reg < 16; ++reg) {
;         const int row = 256 + tm * 256 + 128 * wm + 32 * mi + (reg & 3) + 8 * (reg >> 2) + 4 * h;
;         const int col = nb * 128 + 32 * wn + r;
;         HID[(size_t)row * DFF + col] = f2bf(silu(acc[mi][0][reg]) * acc[mi][1][reg]);
;       }
	s_nop 0
	v_mul_f32_e32 v67, v97, v67
	v_mul_f32_e32 v67, v81, v67
	v_cvt_pk_bf16_f32 v68, v67, s0
	v_mad_i64_i32 v[66:67], s[4:5], v66, s39, v[130:131]
	global_store_short v[66:67], v68, off sc0 sc1
	v_mul_f32_e32 v67, 0xbfb8aa3b, v50
	v_exp_f32_e32 v67, v67
	v_or_b32_e32 v66, 64, v132
	v_add_f32_e32 v67, 1.0, v67
	v_rcp_f32_e32 v67, v67
	s_nop 0
	v_mul_f32_e32 v50, v50, v67
	v_mul_f32_e32 v34, v34, v50
	v_mul_f32_e32 v50, 0xbfb8aa3b, v51
	v_exp_f32_e32 v50, v50
	v_cvt_pk_bf16_f32 v34, v34, s0
	v_mad_i64_i32 v[66:67], s[4:5], v66, s39, v[130:131]
	v_add_f32_e32 v50, 1.0, v50
	v_rcp_f32_e32 v50, v50
	global_store_short v[66:67], v34, off sc0 sc1
	v_or_b32_e32 v34, 0x41, v132
	v_mul_f32_e32 v50, v51, v50
	v_mul_f32_e32 v35, v35, v50
	v_cvt_pk_bf16_f32 v50, v35, s0
	v_mad_i64_i32 v[34:35], s[4:5], v34, s39, v[130:131]
	global_store_short v[34:35], v50, off sc0 sc1
	v_mul_f32_e32 v35, 0xbfb8aa3b, v52
	v_exp_f32_e32 v35, v35
	v_or_b32_e32 v34, 0x42, v132
	v_add_f32_e32 v35, 1.0, v35
	v_rcp_f32_e32 v35, v35
	s_nop 0
	v_mul_f32_e32 v35, v52, v35
	v_mul_f32_e32 v35, v36, v35
	v_cvt_pk_bf16_f32 v36, v35, s0
	v_mad_i64_i32 v[34:35], s[4:5], v34, s39, v[130:131]
	global_store_short v[34:35], v36, off sc0 sc1
	v_mul_f32_e32 v35, 0xbfb8aa3b, v53
	v_exp_f32_e32 v35, v35
	v_or_b32_e32 v34, 0x43, v132
	v_add_f32_e32 v35, 1.0, v35
	v_rcp_f32_e32 v35, v35
	s_nop 0
	v_mul_f32_e32 v35, v53, v35
	v_mul_f32_e32 v35, v37, v35
	v_cvt_pk_bf16_f32 v36, v35, s0
	v_mad_i64_i32 v[34:35], s[4:5], v34, s39, v[130:131]
	global_store_short v[34:35], v36, off sc0 sc1
	v_mul_f32_e32 v35, 0xbfb8aa3b, v54
	v_exp_f32_e32 v35, v35
	v_or_b32_e32 v34, 0x48, v132
	v_add_f32_e32 v35, 1.0, v35
	v_rcp_f32_e32 v35, v35
	s_nop 0
	v_mul_f32_e32 v35, v54, v35
	v_mul_f32_e32 v35, v38, v35
	v_cvt_pk_bf16_f32 v36, v35, s0
	v_mad_i64_i32 v[34:35], s[4:5], v34, s39, v[130:131]
	global_store_short v[34:35], v36, off sc0 sc1
	v_mul_f32_e32 v35, 0xbfb8aa3b, v55
	v_exp_f32_e32 v35, v35
	v_or_b32_e32 v34, 0x49, v132
	v_add_f32_e32 v35, 1.0, v35
	v_rcp_f32_e32 v35, v35
	s_nop 0
	v_mul_f32_e32 v35, v55, v35
	v_mul_f32_e32 v35, v39, v35
	v_cvt_pk_bf16_f32 v36, v35, s0
	v_mad_i64_i32 v[34:35], s[4:5], v34, s39, v[130:131]
	global_store_short v[34:35], v36, off sc0 sc1
	v_mul_f32_e32 v35, 0xbfb8aa3b, v56
	v_exp_f32_e32 v35, v35
	v_or_b32_e32 v34, 0x4a, v132
	v_add_f32_e32 v35, 1.0, v35
	v_rcp_f32_e32 v35, v35
	s_nop 0
	v_mul_f32_e32 v35, v56, v35
	v_mul_f32_e32 v35, v40, v35
	v_cvt_pk_bf16_f32 v36, v35, s0
	v_mad_i64_i32 v[34:35], s[4:5], v34, s39, v[130:131]
	global_store_short v[34:35], v36, off sc0 sc1
	v_mul_f32_e32 v35, 0xbfb8aa3b, v57
	v_exp_f32_e32 v35, v35
	v_or_b32_e32 v34, 0x4b, v132
	v_add_f32_e32 v35, 1.0, v35
	v_rcp_f32_e32 v35, v35
	s_nop 0
	v_mul_f32_e32 v35, v57, v35
	v_mul_f32_e32 v35, v41, v35
	v_cvt_pk_bf16_f32 v36, v35, s0
	v_mad_i64_i32 v[34:35], s[4:5], v34, s39, v[130:131]
	global_store_short v[34:35], v36, off sc0 sc1
	v_mul_f32_e32 v35, 0xbfb8aa3b, v58
	v_exp_f32_e32 v35, v35
	v_or_b32_e32 v34, 0x50, v132
	v_add_f32_e32 v35, 1.0, v35
	v_rcp_f32_e32 v35, v35
	s_nop 0
	v_mul_f32_e32 v35, v58, v35
	v_mul_f32_e32 v35, v42, v35
	v_cvt_pk_bf16_f32 v36, v35, s0
	v_mad_i64_i32 v[34:35], s[4:5], v34, s39, v[130:131]
	global_store_short v[34:35], v36, off sc0 sc1
	v_mul_f32_e32 v35, 0xbfb8aa3b, v59
	v_exp_f32_e32 v35, v35
	v_or_b32_e32 v34, 0x51, v132
	v_add_f32_e32 v35, 1.0, v35
	v_rcp_f32_e32 v35, v35
	s_nop 0
	v_mul_f32_e32 v35, v59, v35
	v_mul_f32_e32 v35, v43, v35
	v_cvt_pk_bf16_f32 v36, v35, s0
	v_mad_i64_i32 v[34:35], s[4:5], v34, s39, v[130:131]
	global_store_short v[34:35], v36, off sc0 sc1
	v_mul_f32_e32 v35, 0xbfb8aa3b, v60
	v_exp_f32_e32 v35, v35
	v_or_b32_e32 v34, 0x52, v132
	v_add_f32_e32 v35, 1.0, v35
	v_rcp_f32_e32 v35, v35
	s_nop 0
	v_mul_f32_e32 v35, v60, v35
	v_mul_f32_e32 v35, v44, v35
	v_cvt_pk_bf16_f32 v36, v35, s0
	v_mad_i64_i32 v[34:35], s[4:5], v34, s39, v[130:131]
	global_store_short v[34:35], v36, off sc0 sc1
	v_mul_f32_e32 v35, 0xbfb8aa3b, v61
	v_exp_f32_e32 v35, v35
	v_or_b32_e32 v34, 0x53, v132
	v_add_f32_e32 v35, 1.0, v35
	v_rcp_f32_e32 v35, v35
	s_nop 0
	v_mul_f32_e32 v35, v61, v35
	v_mul_f32_e32 v35, v45, v35
	v_cvt_pk_bf16_f32 v36, v35, s0
	v_mad_i64_i32 v[34:35], s[4:5], v34, s39, v[130:131]
	global_store_short v[34:35], v36, off sc0 sc1
	v_mul_f32_e32 v35, 0xbfb8aa3b, v62
	v_exp_f32_e32 v35, v35
	v_or_b32_e32 v34, 0x58, v132
	v_add_f32_e32 v35, 1.0, v35
	v_rcp_f32_e32 v35, v35
	s_nop 0
	v_mul_f32_e32 v35, v62, v35
	v_mul_f32_e32 v35, v46, v35
	v_cvt_pk_bf16_f32 v36, v35, s0
	v_mad_i64_i32 v[34:35], s[4:5], v34, s39, v[130:131]
	global_store_short v[34:35], v36, off sc0 sc1
	v_mul_f32_e32 v35, 0xbfb8aa3b, v63
	v_exp_f32_e32 v35, v35
	v_or_b32_e32 v34, 0x59, v132
	v_add_f32_e32 v35, 1.0, v35
	v_rcp_f32_e32 v35, v35
	s_nop 0
	v_mul_f32_e32 v35, v63, v35
	v_mul_f32_e32 v35, v47, v35
	v_cvt_pk_bf16_f32 v36, v35, s0
	v_mad_i64_i32 v[34:35], s[4:5], v34, s39, v[130:131]
	global_store_short v[34:35], v36, off sc0 sc1
	v_mul_f32_e32 v35, 0xbfb8aa3b, v64
	v_exp_f32_e32 v35, v35
	v_or_b32_e32 v34, 0x5a, v132
	v_add_f32_e32 v35, 1.0, v35
	v_rcp_f32_e32 v35, v35
	s_nop 0
	v_mul_f32_e32 v35, v64, v35
	v_mul_f32_e32 v35, v48, v35
	v_cvt_pk_bf16_f32 v36, v35, s0
	v_mad_i64_i32 v[34:35], s[4:5], v34, s39, v[130:131]
	global_store_short v[34:35], v36, off sc0 sc1
	v_mul_f32_e32 v35, 0xbfb8aa3b, v65
	v_exp_f32_e32 v35, v35
	v_or_b32_e32 v34, 0x5b, v132
; DI float silu(float x) { return x * __builtin_amdgcn_rcpf(1.f + __expf(-x)); }
; DI void gateup256(const Params& p, int layer, char* smem) {
;     ...
; #pragma unroll
;     for (int mi = 0; mi < 4; ++mi)
; #pragma unroll
;       for (int reg = 0; reg < 16; ++reg) {
;         const int row = 256 + tm * 256 + 128 * wm + 32 * mi + (reg & 3) + 8 * (reg >> 2) + 4 * h;
;         const int col = nb * 128 + 32 * wn + r;
;         HID[(size_t)row * DFF + col] = f2bf(silu(acc[mi][0][reg]) * acc[mi][1][reg]);
;       }
	v_add_f32_e32 v35, 1.0, v35
	v_rcp_f32_e32 v35, v35
	s_nop 0
	v_mul_f32_e32 v35, v65, v35
	v_mul_f32_e32 v35, v49, v35
	v_cvt_pk_bf16_f32 v36, v35, s0
	v_mad_i64_i32 v[34:35], s[4:5], v34, s39, v[130:131]
	global_store_short v[34:35], v36, off sc0 sc1
	v_mul_f32_e32 v35, 0xbfb8aa3b, v18
	v_exp_f32_e32 v35, v35
	v_or_b32_e32 v34, 0x60, v132
	v_add_f32_e32 v35, 1.0, v35
	v_rcp_f32_e32 v35, v35
	s_nop 0
	v_mul_f32_e32 v18, v18, v35
	v_mul_f32_e32 v2, v2, v18
	v_mul_f32_e32 v18, 0xbfb8aa3b, v19
	v_exp_f32_e32 v18, v18
	v_cvt_pk_bf16_f32 v2, v2, s0
	v_mad_i64_i32 v[34:35], s[4:5], v34, s39, v[130:131]
	v_add_f32_e32 v18, 1.0, v18
	v_rcp_f32_e32 v18, v18
	global_store_short v[34:35], v2, off sc0 sc1
	v_or_b32_e32 v2, 0x61, v132
	v_mul_f32_e32 v18, v19, v18
	v_mul_f32_e32 v3, v3, v18
	v_cvt_pk_bf16_f32 v18, v3, s0
	v_mad_i64_i32 v[2:3], s[4:5], v2, s39, v[130:131]
	global_store_short v[2:3], v18, off sc0 sc1
	v_mul_f32_e32 v3, 0xbfb8aa3b, v20
	v_exp_f32_e32 v3, v3
	v_or_b32_e32 v2, 0x62, v132
	v_add_f32_e32 v3, 1.0, v3
	v_rcp_f32_e32 v3, v3
	s_nop 0
	v_mul_f32_e32 v3, v20, v3
	v_mul_f32_e32 v3, v4, v3
	v_cvt_pk_bf16_f32 v4, v3, s0
	v_mad_i64_i32 v[2:3], s[4:5], v2, s39, v[130:131]
	global_store_short v[2:3], v4, off sc0 sc1
	v_mul_f32_e32 v3, 0xbfb8aa3b, v21
	v_exp_f32_e32 v3, v3
	v_or_b32_e32 v2, 0x63, v132
	v_add_f32_e32 v3, 1.0, v3
	v_rcp_f32_e32 v3, v3
	s_nop 0
	v_mul_f32_e32 v3, v21, v3
	v_mul_f32_e32 v3, v5, v3
	v_cvt_pk_bf16_f32 v4, v3, s0
	v_mad_i64_i32 v[2:3], s[4:5], v2, s39, v[130:131]
	global_store_short v[2:3], v4, off sc0 sc1
	v_mul_f32_e32 v3, 0xbfb8aa3b, v22
	v_exp_f32_e32 v3, v3
	v_or_b32_e32 v2, 0x68, v132
	v_add_f32_e32 v3, 1.0, v3
	v_rcp_f32_e32 v3, v3
	s_nop 0
	v_mul_f32_e32 v3, v22, v3
	v_mul_f32_e32 v3, v6, v3
	v_cvt_pk_bf16_f32 v4, v3, s0
	v_mad_i64_i32 v[2:3], s[4:5], v2, s39, v[130:131]
	global_store_short v[2:3], v4, off sc0 sc1
	v_mul_f32_e32 v3, 0xbfb8aa3b, v23
	v_exp_f32_e32 v3, v3
	v_or_b32_e32 v2, 0x69, v132
	v_add_f32_e32 v3, 1.0, v3
	v_rcp_f32_e32 v3, v3
	s_nop 0
	v_mul_f32_e32 v3, v23, v3
	v_mul_f32_e32 v3, v7, v3
	v_cvt_pk_bf16_f32 v4, v3, s0
	v_mad_i64_i32 v[2:3], s[4:5], v2, s39, v[130:131]
	global_store_short v[2:3], v4, off sc0 sc1
	v_mul_f32_e32 v3, 0xbfb8aa3b, v24
	v_exp_f32_e32 v3, v3
	v_or_b32_e32 v2, 0x6a, v132
	v_add_f32_e32 v3, 1.0, v3
	v_rcp_f32_e32 v3, v3
	s_nop 0
	v_mul_f32_e32 v3, v24, v3
	v_mul_f32_e32 v3, v8, v3
	v_cvt_pk_bf16_f32 v4, v3, s0
	v_mad_i64_i32 v[2:3], s[4:5], v2, s39, v[130:131]
	global_store_short v[2:3], v4, off sc0 sc1
	v_mul_f32_e32 v3, 0xbfb8aa3b, v25
	v_exp_f32_e32 v3, v3
	v_or_b32_e32 v2, 0x6b, v132
	v_add_f32_e32 v3, 1.0, v3
	v_rcp_f32_e32 v3, v3
	s_nop 0
	v_mul_f32_e32 v3, v25, v3
	v_mul_f32_e32 v3, v9, v3
	v_cvt_pk_bf16_f32 v4, v3, s0
	v_mad_i64_i32 v[2:3], s[4:5], v2, s39, v[130:131]
	global_store_short v[2:3], v4, off sc0 sc1
	v_mul_f32_e32 v3, 0xbfb8aa3b, v26
	v_exp_f32_e32 v3, v3
	v_or_b32_e32 v2, 0x70, v132
	v_add_f32_e32 v3, 1.0, v3
	v_rcp_f32_e32 v3, v3
	s_nop 0
	v_mul_f32_e32 v3, v26, v3
	v_mul_f32_e32 v3, v10, v3
	v_cvt_pk_bf16_f32 v4, v3, s0
	v_mad_i64_i32 v[2:3], s[4:5], v2, s39, v[130:131]
	global_store_short v[2:3], v4, off sc0 sc1
	v_mul_f32_e32 v3, 0xbfb8aa3b, v27
	v_exp_f32_e32 v3, v3
	v_or_b32_e32 v2, 0x71, v132
	v_add_f32_e32 v3, 1.0, v3
	v_rcp_f32_e32 v3, v3
	s_nop 0
	v_mul_f32_e32 v3, v27, v3
	v_mul_f32_e32 v3, v11, v3
	v_cvt_pk_bf16_f32 v4, v3, s0
	v_mad_i64_i32 v[2:3], s[4:5], v2, s39, v[130:131]
	global_store_short v[2:3], v4, off sc0 sc1
	v_mul_f32_e32 v3, 0xbfb8aa3b, v28
	v_exp_f32_e32 v3, v3
	v_or_b32_e32 v2, 0x72, v132
	v_add_f32_e32 v3, 1.0, v3
	v_rcp_f32_e32 v3, v3
	s_nop 0
	v_mul_f32_e32 v3, v28, v3
	v_mul_f32_e32 v3, v12, v3
	v_cvt_pk_bf16_f32 v4, v3, s0
	v_mad_i64_i32 v[2:3], s[4:5], v2, s39, v[130:131]
	global_store_short v[2:3], v4, off sc0 sc1
	v_mul_f32_e32 v3, 0xbfb8aa3b, v29
	v_exp_f32_e32 v3, v3
	v_or_b32_e32 v2, 0x73, v132
	v_add_f32_e32 v3, 1.0, v3
	v_rcp_f32_e32 v3, v3
	s_nop 0
	v_mul_f32_e32 v3, v29, v3
	v_mul_f32_e32 v3, v13, v3
	v_cvt_pk_bf16_f32 v4, v3, s0
	v_mad_i64_i32 v[2:3], s[4:5], v2, s39, v[130:131]
	global_store_short v[2:3], v4, off sc0 sc1
	v_mul_f32_e32 v3, 0xbfb8aa3b, v30
	v_exp_f32_e32 v3, v3
	v_or_b32_e32 v2, 0x78, v132
	v_add_f32_e32 v3, 1.0, v3
	v_rcp_f32_e32 v3, v3
	s_nop 0
	v_mul_f32_e32 v3, v30, v3
	v_mul_f32_e32 v3, v14, v3
	v_cvt_pk_bf16_f32 v4, v3, s0
	v_mad_i64_i32 v[2:3], s[4:5], v2, s39, v[130:131]
	global_store_short v[2:3], v4, off sc0 sc1
	v_mul_f32_e32 v3, 0xbfb8aa3b, v31
	v_exp_f32_e32 v3, v3
	v_or_b32_e32 v2, 0x79, v132
	v_add_f32_e32 v3, 1.0, v3
	v_rcp_f32_e32 v3, v3
	s_nop 0
	v_mul_f32_e32 v3, v31, v3
	v_mul_f32_e32 v3, v15, v3
	v_cvt_pk_bf16_f32 v4, v3, s0
	v_mad_i64_i32 v[2:3], s[4:5], v2, s39, v[130:131]
	global_store_short v[2:3], v4, off sc0 sc1
	v_mul_f32_e32 v3, 0xbfb8aa3b, v32
	v_exp_f32_e32 v3, v3
	v_or_b32_e32 v2, 0x7a, v132
	v_add_f32_e32 v3, 1.0, v3
	v_rcp_f32_e32 v3, v3
	s_nop 0
	v_mul_f32_e32 v3, v32, v3
	v_mul_f32_e32 v3, v16, v3
	v_cvt_pk_bf16_f32 v4, v3, s0
	v_mad_i64_i32 v[2:3], s[4:5], v2, s39, v[130:131]
	global_store_short v[2:3], v4, off sc0 sc1
	v_mul_f32_e32 v3, 0xbfb8aa3b, v33
	v_exp_f32_e32 v3, v3
	v_or_b32_e32 v2, 0x7b, v132
	v_add_f32_e32 v3, 1.0, v3
	v_rcp_f32_e32 v3, v3
	s_nop 0
	v_mul_f32_e32 v3, v33, v3
	v_mul_f32_e32 v3, v17, v3
	v_cvt_pk_bf16_f32 v4, v3, s0
	v_mad_i64_i32 v[2:3], s[4:5], v2, s39, v[130:131]
	global_store_short v[2:3], v4, off sc0 sc1
	s_branch .LBB0_1559

; DI void down256(const Params& p, int layer, char* smem) {
;     ...
; #pragma unroll
;     for (int mi = 0; mi < 4; ++mi)
; #pragma unroll
;       for (int ni = 0; ni < 2; ++ni) {
;         const int col = tn * 256 + 64 * wn + 32 * ni + r;
;         const float gg = g2[col];
; #pragma unroll
;         for (int reg = 0; reg < 16; ++reg) {
;           const int row = 256 + tm * 256 + 128 * wm + 32 * mi + (reg & 3) + 8 * (reg >> 2) + 4 * h;
;           X[(size_t)row * DM + col] += gg * acc[mi][ni][reg];
;         }
;       }
.LBB0_1646:
	s_waitcnt vmcnt(0)
	v_and_b32_e32 v130, 0xdf, v0
	v_or_b32_e32 v130, s12, v130
	v_lshlrev_b32_e32 v130, 2, v130
	global_load_dword v137, v130, s[0:1]
	global_load_dword v138, v130, s[0:1] offset:128
	v_ashrrev_i32_e32 v131, 1, v0
	v_and_b32_e32 v131, 0xffffff80, v131
	v_add_u32_e32 v131, s11, v131
	v_lshrrev_b32_e32 v132, 3, v0
	v_and_or_b32 v131, v132, 4, v131
	v_lshl_add_u32 v133, v131, 13, v130
	v_add_u32_e32 v134, 0x2000, v133
	v_add_u32_e32 v135, 0x4000, v133
	v_add_u32_e32 v136, 0x6000, v133
	s_mov_b64 s[52:53], s[90:91]
	s_mov_b64 s[54:55], s[90:91]
	s_add_i32 s10, s10, 1
	s_add_u32 s56, s52, 0x0
	s_addc_u32 s57, s53, 0
	global_load_dword v193, v133, s[56:57]
	global_load_dword v194, v133, s[56:57] offset:128
	global_load_dword v195, v134, s[56:57]
	global_load_dword v196, v134, s[56:57] offset:128
	global_load_dword v197, v135, s[56:57]
	global_load_dword v198, v135, s[56:57] offset:128
	global_load_dword v199, v136, s[56:57]
	global_load_dword v200, v136, s[56:57] offset:128
	s_add_u32 s56, s52, 0x10000
	s_addc_u32 s57, s53, 0
	global_load_dword v201, v133, s[56:57]
	global_load_dword v202, v133, s[56:57] offset:128
	global_load_dword v203, v134, s[56:57]
	global_load_dword v204, v134, s[56:57] offset:128
	global_load_dword v205, v135, s[56:57]
	global_load_dword v206, v135, s[56:57] offset:128
	global_load_dword v207, v136, s[56:57]
	global_load_dword v208, v136, s[56:57] offset:128
	s_add_u32 s56, s52, 0x20000
	s_addc_u32 s57, s53, 0
	global_load_dword v209, v133, s[56:57]
	global_load_dword v210, v133, s[56:57] offset:128
	global_load_dword v211, v134, s[56:57]
	global_load_dword v212, v134, s[56:57] offset:128
	global_load_dword v213, v135, s[56:57]
	global_load_dword v214, v135, s[56:57] offset:128
	global_load_dword v215, v136, s[56:57]
	global_load_dword v216, v136, s[56:57] offset:128
	s_add_u32 s56, s52, 0x30000
	s_addc_u32 s57, s53, 0
	global_load_dword v217, v133, s[56:57]
	global_load_dword v218, v133, s[56:57] offset:128
	global_load_dword v219, v134, s[56:57]
	global_load_dword v220, v134, s[56:57] offset:128
	global_load_dword v221, v135, s[56:57]
	global_load_dword v222, v135, s[56:57] offset:128
	global_load_dword v223, v136, s[56:57]
	global_load_dword v224, v136, s[56:57] offset:128
	s_waitcnt vmcnt(16)
	v_fmac_f32_e32 v193, v114, v137
	v_fmac_f32_e32 v194, v98, v138
	v_fmac_f32_e32 v195, v115, v137
	v_fmac_f32_e32 v196, v99, v138
	v_fmac_f32_e32 v197, v116, v137
	v_fmac_f32_e32 v198, v100, v138
	v_fmac_f32_e32 v199, v117, v137
	v_fmac_f32_e32 v200, v101, v138
	v_fmac_f32_e32 v201, v118, v137
	v_fmac_f32_e32 v202, v102, v138
	v_fmac_f32_e32 v203, v119, v137
	v_fmac_f32_e32 v204, v103, v138
	v_fmac_f32_e32 v205, v120, v137
	v_fmac_f32_e32 v206, v104, v138
	v_fmac_f32_e32 v207, v121, v137
	v_fmac_f32_e32 v208, v105, v138
	s_add_u32 s56, s52, 0x40000
	s_addc_u32 s57, s53, 0
	global_load_dword v225, v133, s[56:57]
	global_load_dword v226, v133, s[56:57] offset:128
	global_load_dword v227, v134, s[56:57]
	global_load_dword v228, v134, s[56:57] offset:128
	global_load_dword v229, v135, s[56:57]
	global_load_dword v230, v135, s[56:57] offset:128
	global_load_dword v231, v136, s[56:57]
	global_load_dword v237, v136, s[56:57] offset:128
	s_add_u32 s56, s52, 0x50000
	s_addc_u32 s57, s53, 0
	global_load_dword v238, v133, s[56:57]
	global_load_dword v239, v133, s[56:57] offset:128
	global_load_dword v240, v134, s[56:57]
	global_load_dword v241, v134, s[56:57] offset:128
	global_load_dword v242, v135, s[56:57]
	global_load_dword v243, v135, s[56:57] offset:128
	global_load_dword v244, v136, s[56:57]
	global_load_dword v245, v136, s[56:57] offset:128
	s_add_u32 s58, s54, 0x0
	s_addc_u32 s59, s55, 0
	global_store_dword v133, v193, s[58:59] sc0 sc1
	global_store_dword v133, v194, s[58:59] offset:128 sc0 sc1
	global_store_dword v134, v195, s[58:59] sc0 sc1
	global_store_dword v134, v196, s[58:59] offset:128 sc0 sc1
	global_store_dword v135, v197, s[58:59] sc0 sc1
	global_store_dword v135, v198, s[58:59] offset:128 sc0 sc1
	global_store_dword v136, v199, s[58:59] sc0 sc1
	global_store_dword v136, v200, s[58:59] offset:128 sc0 sc1
	s_add_u32 s58, s54, 0x10000
	s_addc_u32 s59, s55, 0
	global_store_dword v133, v201, s[58:59] sc0 sc1
	global_store_dword v133, v202, s[58:59] offset:128 sc0 sc1
	global_store_dword v134, v203, s[58:59] sc0 sc1
	global_store_dword v134, v204, s[58:59] offset:128 sc0 sc1
	global_store_dword v135, v205, s[58:59] sc0 sc1
	global_store_dword v135, v206, s[58:59] offset:128 sc0 sc1
	global_store_dword v136, v207, s[58:59] sc0 sc1
	global_store_dword v136, v208, s[58:59] offset:128 sc0 sc1
	s_waitcnt vmcnt(32)
; DI void down256(const Params& p, int layer, char* smem) {
;     ...
; #pragma unroll
;     for (int mi = 0; mi < 4; ++mi)
; #pragma unroll
;       for (int ni = 0; ni < 2; ++ni) {
;         const int col = tn * 256 + 64 * wn + 32 * ni + r;
;         const float gg = g2[col];
; #pragma unroll
;         for (int reg = 0; reg < 16; ++reg) {
;           const int row = 256 + tm * 256 + 128 * wm + 32 * mi + (reg & 3) + 8 * (reg >> 2) + 4 * h;
;           X[(size_t)row * DM + col] += gg * acc[mi][ni][reg];
;         }
;       }
	v_fmac_f32_e32 v209, v122, v137
	v_fmac_f32_e32 v210, v106, v138
	v_fmac_f32_e32 v211, v123, v137
	v_fmac_f32_e32 v212, v107, v138
	v_fmac_f32_e32 v213, v124, v137
	v_fmac_f32_e32 v214, v108, v138
	v_fmac_f32_e32 v215, v125, v137
	v_fmac_f32_e32 v216, v109, v138
	v_fmac_f32_e32 v217, v126, v137
	v_fmac_f32_e32 v218, v110, v138
	v_fmac_f32_e32 v219, v127, v137
	v_fmac_f32_e32 v220, v111, v138
	v_fmac_f32_e32 v221, v128, v137
	v_fmac_f32_e32 v222, v112, v138
	v_fmac_f32_e32 v223, v129, v137
	v_fmac_f32_e32 v224, v113, v138
	s_add_u32 s56, s52, 0x60000
	s_addc_u32 s57, s53, 0
	global_load_dword v193, v133, s[56:57]
	global_load_dword v194, v133, s[56:57] offset:128
	global_load_dword v195, v134, s[56:57]
	global_load_dword v196, v134, s[56:57] offset:128
	global_load_dword v197, v135, s[56:57]
	global_load_dword v198, v135, s[56:57] offset:128
	global_load_dword v199, v136, s[56:57]
	global_load_dword v200, v136, s[56:57] offset:128
	s_add_u32 s56, s52, 0x70000
	s_addc_u32 s57, s53, 0
	global_load_dword v201, v133, s[56:57]
	global_load_dword v202, v133, s[56:57] offset:128
	global_load_dword v203, v134, s[56:57]
	global_load_dword v204, v134, s[56:57] offset:128
	global_load_dword v205, v135, s[56:57]
	global_load_dword v206, v135, s[56:57] offset:128
	global_load_dword v207, v136, s[56:57]
	global_load_dword v208, v136, s[56:57] offset:128
	s_add_u32 s58, s54, 0x20000
	s_addc_u32 s59, s55, 0
	global_store_dword v133, v209, s[58:59] sc0 sc1
	global_store_dword v133, v210, s[58:59] offset:128 sc0 sc1
	global_store_dword v134, v211, s[58:59] sc0 sc1
	global_store_dword v134, v212, s[58:59] offset:128 sc0 sc1
	global_store_dword v135, v213, s[58:59] sc0 sc1
	global_store_dword v135, v214, s[58:59] offset:128 sc0 sc1
	global_store_dword v136, v215, s[58:59] sc0 sc1
	global_store_dword v136, v216, s[58:59] offset:128 sc0 sc1
	s_add_u32 s58, s54, 0x30000
	s_addc_u32 s59, s55, 0
	global_store_dword v133, v217, s[58:59] sc0 sc1
	global_store_dword v133, v218, s[58:59] offset:128 sc0 sc1
	global_store_dword v134, v219, s[58:59] sc0 sc1
	global_store_dword v134, v220, s[58:59] offset:128 sc0 sc1
	global_store_dword v135, v221, s[58:59] sc0 sc1
	global_store_dword v135, v222, s[58:59] offset:128 sc0 sc1
	global_store_dword v136, v223, s[58:59] sc0 sc1
	global_store_dword v136, v224, s[58:59] offset:128 sc0 sc1
	s_waitcnt vmcnt(48)
	v_fmac_f32_e32 v225, v82, v137
	v_fmac_f32_e32 v226, v66, v138
	v_fmac_f32_e32 v227, v83, v137
	v_fmac_f32_e32 v228, v67, v138
	v_fmac_f32_e32 v229, v84, v137
	v_fmac_f32_e32 v230, v68, v138
	v_fmac_f32_e32 v231, v85, v137
	v_fmac_f32_e32 v237, v69, v138
	v_fmac_f32_e32 v238, v86, v137
	v_fmac_f32_e32 v239, v70, v138
	v_fmac_f32_e32 v240, v87, v137
	v_fmac_f32_e32 v241, v71, v138
	v_fmac_f32_e32 v242, v88, v137
	v_fmac_f32_e32 v243, v72, v138
	v_fmac_f32_e32 v244, v89, v137
	v_fmac_f32_e32 v245, v73, v138
	s_add_u32 s56, s52, 0x80000
	s_addc_u32 s57, s53, 0
	global_load_dword v209, v133, s[56:57]
	global_load_dword v210, v133, s[56:57] offset:128
	global_load_dword v211, v134, s[56:57]
	global_load_dword v212, v134, s[56:57] offset:128
	global_load_dword v213, v135, s[56:57]
	global_load_dword v214, v135, s[56:57] offset:128
	global_load_dword v215, v136, s[56:57]
	global_load_dword v216, v136, s[56:57] offset:128
	s_add_u32 s56, s52, 0x90000
	s_addc_u32 s57, s53, 0
	global_load_dword v217, v133, s[56:57]
	global_load_dword v218, v133, s[56:57] offset:128
	global_load_dword v219, v134, s[56:57]
	global_load_dword v220, v134, s[56:57] offset:128
	global_load_dword v221, v135, s[56:57]
	global_load_dword v222, v135, s[56:57] offset:128
	global_load_dword v223, v136, s[56:57]
	global_load_dword v224, v136, s[56:57] offset:128
	s_add_u32 s58, s54, 0x40000
	s_addc_u32 s59, s55, 0
	global_store_dword v133, v225, s[58:59] sc0 sc1
	global_store_dword v133, v226, s[58:59] offset:128 sc0 sc1
	global_store_dword v134, v227, s[58:59] sc0 sc1
	global_store_dword v134, v228, s[58:59] offset:128 sc0 sc1
	global_store_dword v135, v229, s[58:59] sc0 sc1
	global_store_dword v135, v230, s[58:59] offset:128 sc0 sc1
	global_store_dword v136, v231, s[58:59] sc0 sc1
	global_store_dword v136, v237, s[58:59] offset:128 sc0 sc1
	s_add_u32 s58, s54, 0x50000
	s_addc_u32 s59, s55, 0
	global_store_dword v133, v238, s[58:59] sc0 sc1
	global_store_dword v133, v239, s[58:59] offset:128 sc0 sc1
	global_store_dword v134, v240, s[58:59] sc0 sc1
	global_store_dword v134, v241, s[58:59] offset:128 sc0 sc1
	global_store_dword v135, v242, s[58:59] sc0 sc1
	global_store_dword v135, v243, s[58:59] offset:128 sc0 sc1
	global_store_dword v136, v244, s[58:59] sc0 sc1
	global_store_dword v136, v245, s[58:59] offset:128 sc0 sc1
	s_waitcnt vmcnt(48)
; DI void down256(const Params& p, int layer, char* smem) {
;     ...
; #pragma unroll
;     for (int mi = 0; mi < 4; ++mi)
; #pragma unroll
;       for (int ni = 0; ni < 2; ++ni) {
;         const int col = tn * 256 + 64 * wn + 32 * ni + r;
;         const float gg = g2[col];
; #pragma unroll
;         for (int reg = 0; reg < 16; ++reg) {
;           const int row = 256 + tm * 256 + 128 * wm + 32 * mi + (reg & 3) + 8 * (reg >> 2) + 4 * h;
;           X[(size_t)row * DM + col] += gg * acc[mi][ni][reg];
;         }
;       }
	v_fmac_f32_e32 v193, v90, v137
	v_fmac_f32_e32 v194, v74, v138
	v_fmac_f32_e32 v195, v91, v137
	v_fmac_f32_e32 v196, v75, v138
	v_fmac_f32_e32 v197, v92, v137
	v_fmac_f32_e32 v198, v76, v138
	v_fmac_f32_e32 v199, v93, v137
	v_fmac_f32_e32 v200, v77, v138
	v_fmac_f32_e32 v201, v94, v137
	v_fmac_f32_e32 v202, v78, v138
	v_fmac_f32_e32 v203, v95, v137
	v_fmac_f32_e32 v204, v79, v138
	v_fmac_f32_e32 v205, v96, v137
	v_fmac_f32_e32 v206, v80, v138
	v_fmac_f32_e32 v207, v97, v137
	v_fmac_f32_e32 v208, v81, v138
	s_add_u32 s56, s52, 0xa0000
	s_addc_u32 s57, s53, 0
	global_load_dword v225, v133, s[56:57]
	global_load_dword v226, v133, s[56:57] offset:128
	global_load_dword v227, v134, s[56:57]
	global_load_dword v228, v134, s[56:57] offset:128
	global_load_dword v229, v135, s[56:57]
	global_load_dword v230, v135, s[56:57] offset:128
	global_load_dword v231, v136, s[56:57]
	global_load_dword v237, v136, s[56:57] offset:128
	s_add_u32 s56, s52, 0xb0000
	s_addc_u32 s57, s53, 0
	global_load_dword v238, v133, s[56:57]
	global_load_dword v239, v133, s[56:57] offset:128
	global_load_dword v240, v134, s[56:57]
	global_load_dword v241, v134, s[56:57] offset:128
	global_load_dword v242, v135, s[56:57]
	global_load_dword v243, v135, s[56:57] offset:128
	global_load_dword v244, v136, s[56:57]
	global_load_dword v245, v136, s[56:57] offset:128
	s_add_u32 s58, s54, 0x60000
	s_addc_u32 s59, s55, 0
	global_store_dword v133, v193, s[58:59] sc0 sc1
	global_store_dword v133, v194, s[58:59] offset:128 sc0 sc1
	global_store_dword v134, v195, s[58:59] sc0 sc1
	global_store_dword v134, v196, s[58:59] offset:128 sc0 sc1
	global_store_dword v135, v197, s[58:59] sc0 sc1
	global_store_dword v135, v198, s[58:59] offset:128 sc0 sc1
	global_store_dword v136, v199, s[58:59] sc0 sc1
	global_store_dword v136, v200, s[58:59] offset:128 sc0 sc1
	s_add_u32 s58, s54, 0x70000
	s_addc_u32 s59, s55, 0
	global_store_dword v133, v201, s[58:59] sc0 sc1
	global_store_dword v133, v202, s[58:59] offset:128 sc0 sc1
	global_store_dword v134, v203, s[58:59] sc0 sc1
	global_store_dword v134, v204, s[58:59] offset:128 sc0 sc1
	global_store_dword v135, v205, s[58:59] sc0 sc1
	global_store_dword v135, v206, s[58:59] offset:128 sc0 sc1
	global_store_dword v136, v207, s[58:59] sc0 sc1
	global_store_dword v136, v208, s[58:59] offset:128 sc0 sc1
	s_waitcnt vmcnt(48)
	v_fmac_f32_e32 v209, v50, v137
	v_fmac_f32_e32 v210, v34, v138
	v_fmac_f32_e32 v211, v51, v137
	v_fmac_f32_e32 v212, v35, v138
	v_fmac_f32_e32 v213, v52, v137
	v_fmac_f32_e32 v214, v36, v138
	v_fmac_f32_e32 v215, v53, v137
	v_fmac_f32_e32 v216, v37, v138
	v_fmac_f32_e32 v217, v54, v137
	v_fmac_f32_e32 v218, v38, v138
	v_fmac_f32_e32 v219, v55, v137
	v_fmac_f32_e32 v220, v39, v138
	v_fmac_f32_e32 v221, v56, v137
	v_fmac_f32_e32 v222, v40, v138
	v_fmac_f32_e32 v223, v57, v137
	v_fmac_f32_e32 v224, v41, v138
	s_add_u32 s56, s52, 0xc0000
	s_addc_u32 s57, s53, 0
	global_load_dword v193, v133, s[56:57]
	global_load_dword v194, v133, s[56:57] offset:128
	global_load_dword v195, v134, s[56:57]
	global_load_dword v196, v134, s[56:57] offset:128
	global_load_dword v197, v135, s[56:57]
	global_load_dword v198, v135, s[56:57] offset:128
	global_load_dword v199, v136, s[56:57]
	global_load_dword v200, v136, s[56:57] offset:128
	s_add_u32 s56, s52, 0xd0000
	s_addc_u32 s57, s53, 0
	global_load_dword v201, v133, s[56:57]
	global_load_dword v202, v133, s[56:57] offset:128
	global_load_dword v203, v134, s[56:57]
	global_load_dword v204, v134, s[56:57] offset:128
	global_load_dword v205, v135, s[56:57]
	global_load_dword v206, v135, s[56:57] offset:128
	global_load_dword v207, v136, s[56:57]
	global_load_dword v208, v136, s[56:57] offset:128
	s_add_u32 s58, s54, 0x80000
	s_addc_u32 s59, s55, 0
	global_store_dword v133, v209, s[58:59] sc0 sc1
	global_store_dword v133, v210, s[58:59] offset:128 sc0 sc1
	global_store_dword v134, v211, s[58:59] sc0 sc1
	global_store_dword v134, v212, s[58:59] offset:128 sc0 sc1
	global_store_dword v135, v213, s[58:59] sc0 sc1
	global_store_dword v135, v214, s[58:59] offset:128 sc0 sc1
	global_store_dword v136, v215, s[58:59] sc0 sc1
	global_store_dword v136, v216, s[58:59] offset:128 sc0 sc1
	s_add_u32 s58, s54, 0x90000
	s_addc_u32 s59, s55, 0
	global_store_dword v133, v217, s[58:59] sc0 sc1
	global_store_dword v133, v218, s[58:59] offset:128 sc0 sc1
	global_store_dword v134, v219, s[58:59] sc0 sc1
	global_store_dword v134, v220, s[58:59] offset:128 sc0 sc1
	global_store_dword v135, v221, s[58:59] sc0 sc1
	global_store_dword v135, v222, s[58:59] offset:128 sc0 sc1
	global_store_dword v136, v223, s[58:59] sc0 sc1
	global_store_dword v136, v224, s[58:59] offset:128 sc0 sc1
	s_waitcnt vmcnt(48)
; DI void down256(const Params& p, int layer, char* smem) {
;     ...
; #pragma unroll
;     for (int mi = 0; mi < 4; ++mi)
; #pragma unroll
;       for (int ni = 0; ni < 2; ++ni) {
;         const int col = tn * 256 + 64 * wn + 32 * ni + r;
;         const float gg = g2[col];
; #pragma unroll
;         for (int reg = 0; reg < 16; ++reg) {
;           const int row = 256 + tm * 256 + 128 * wm + 32 * mi + (reg & 3) + 8 * (reg >> 2) + 4 * h;
;           X[(size_t)row * DM + col] += gg * acc[mi][ni][reg];
;         }
;       }
	v_fmac_f32_e32 v225, v58, v137
	v_fmac_f32_e32 v226, v42, v138
	v_fmac_f32_e32 v227, v59, v137
	v_fmac_f32_e32 v228, v43, v138
	v_fmac_f32_e32 v229, v60, v137
	v_fmac_f32_e32 v230, v44, v138
	v_fmac_f32_e32 v231, v61, v137
	v_fmac_f32_e32 v237, v45, v138
	v_fmac_f32_e32 v238, v62, v137
	v_fmac_f32_e32 v239, v46, v138
	v_fmac_f32_e32 v240, v63, v137
	v_fmac_f32_e32 v241, v47, v138
	v_fmac_f32_e32 v242, v64, v137
	v_fmac_f32_e32 v243, v48, v138
	v_fmac_f32_e32 v244, v65, v137
	v_fmac_f32_e32 v245, v49, v138
	s_add_u32 s56, s52, 0xe0000
	s_addc_u32 s57, s53, 0
	global_load_dword v209, v133, s[56:57]
	global_load_dword v210, v133, s[56:57] offset:128
	global_load_dword v211, v134, s[56:57]
	global_load_dword v212, v134, s[56:57] offset:128
	global_load_dword v213, v135, s[56:57]
	global_load_dword v214, v135, s[56:57] offset:128
	global_load_dword v215, v136, s[56:57]
	global_load_dword v216, v136, s[56:57] offset:128
	s_add_u32 s56, s52, 0xf0000
	s_addc_u32 s57, s53, 0
	global_load_dword v217, v133, s[56:57]
	global_load_dword v218, v133, s[56:57] offset:128
	global_load_dword v219, v134, s[56:57]
	global_load_dword v220, v134, s[56:57] offset:128
	global_load_dword v221, v135, s[56:57]
	global_load_dword v222, v135, s[56:57] offset:128
	global_load_dword v223, v136, s[56:57]
	global_load_dword v224, v136, s[56:57] offset:128
	s_add_u32 s58, s54, 0xa0000
	s_addc_u32 s59, s55, 0
	global_store_dword v133, v225, s[58:59] sc0 sc1
	global_store_dword v133, v226, s[58:59] offset:128 sc0 sc1
	global_store_dword v134, v227, s[58:59] sc0 sc1
	global_store_dword v134, v228, s[58:59] offset:128 sc0 sc1
	global_store_dword v135, v229, s[58:59] sc0 sc1
	global_store_dword v135, v230, s[58:59] offset:128 sc0 sc1
	global_store_dword v136, v231, s[58:59] sc0 sc1
	global_store_dword v136, v237, s[58:59] offset:128 sc0 sc1
	s_add_u32 s58, s54, 0xb0000
	s_addc_u32 s59, s55, 0
	global_store_dword v133, v238, s[58:59] sc0 sc1
	global_store_dword v133, v239, s[58:59] offset:128 sc0 sc1
	global_store_dword v134, v240, s[58:59] sc0 sc1
	global_store_dword v134, v241, s[58:59] offset:128 sc0 sc1
	global_store_dword v135, v242, s[58:59] sc0 sc1
	global_store_dword v135, v243, s[58:59] offset:128 sc0 sc1
	global_store_dword v136, v244, s[58:59] sc0 sc1
	global_store_dword v136, v245, s[58:59] offset:128 sc0 sc1
	s_waitcnt vmcnt(48)
	v_fmac_f32_e32 v193, v18, v137
	v_fmac_f32_e32 v194, v2, v138
	v_fmac_f32_e32 v195, v19, v137
	v_fmac_f32_e32 v196, v3, v138
	v_fmac_f32_e32 v197, v20, v137
	v_fmac_f32_e32 v198, v4, v138
	v_fmac_f32_e32 v199, v21, v137
	v_fmac_f32_e32 v200, v5, v138
	v_fmac_f32_e32 v201, v22, v137
	v_fmac_f32_e32 v202, v6, v138
	v_fmac_f32_e32 v203, v23, v137
	v_fmac_f32_e32 v204, v7, v138
	v_fmac_f32_e32 v205, v24, v137
	v_fmac_f32_e32 v206, v8, v138
	v_fmac_f32_e32 v207, v25, v137
	v_fmac_f32_e32 v208, v9, v138
	s_add_u32 s58, s54, 0xc0000
	s_addc_u32 s59, s55, 0
	global_store_dword v133, v193, s[58:59] sc0 sc1
	global_store_dword v133, v194, s[58:59] offset:128 sc0 sc1
	global_store_dword v134, v195, s[58:59] sc0 sc1
	global_store_dword v134, v196, s[58:59] offset:128 sc0 sc1
	global_store_dword v135, v197, s[58:59] sc0 sc1
	global_store_dword v135, v198, s[58:59] offset:128 sc0 sc1
	global_store_dword v136, v199, s[58:59] sc0 sc1
	global_store_dword v136, v200, s[58:59] offset:128 sc0 sc1
	s_add_u32 s58, s54, 0xd0000
	s_addc_u32 s59, s55, 0
	global_store_dword v133, v201, s[58:59] sc0 sc1
	global_store_dword v133, v202, s[58:59] offset:128 sc0 sc1
	global_store_dword v134, v203, s[58:59] sc0 sc1
	global_store_dword v134, v204, s[58:59] offset:128 sc0 sc1
	global_store_dword v135, v205, s[58:59] sc0 sc1
	global_store_dword v135, v206, s[58:59] offset:128 sc0 sc1
	global_store_dword v136, v207, s[58:59] sc0 sc1
	global_store_dword v136, v208, s[58:59] offset:128 sc0 sc1
	s_waitcnt vmcnt(32)
	v_fmac_f32_e32 v209, v26, v137
	v_fmac_f32_e32 v210, v10, v138
	v_fmac_f32_e32 v211, v27, v137
	v_fmac_f32_e32 v212, v11, v138
	v_fmac_f32_e32 v213, v28, v137
	v_fmac_f32_e32 v214, v12, v138
	v_fmac_f32_e32 v215, v29, v137
	v_fmac_f32_e32 v216, v13, v138
	v_fmac_f32_e32 v217, v30, v137
	v_fmac_f32_e32 v218, v14, v138
	v_fmac_f32_e32 v219, v31, v137
	v_fmac_f32_e32 v220, v15, v138
	v_fmac_f32_e32 v221, v32, v137
	v_fmac_f32_e32 v222, v16, v138
	v_fmac_f32_e32 v223, v33, v137
	v_fmac_f32_e32 v224, v17, v138
	s_add_u32 s58, s54, 0xe0000
	s_addc_u32 s59, s55, 0
	global_store_dword v133, v209, s[58:59] sc0 sc1
	global_store_dword v133, v210, s[58:59] offset:128 sc0 sc1
	global_store_dword v134, v211, s[58:59] sc0 sc1
	global_store_dword v134, v212, s[58:59] offset:128 sc0 sc1
	global_store_dword v135, v213, s[58:59] sc0 sc1
	global_store_dword v135, v214, s[58:59] offset:128 sc0 sc1
	global_store_dword v136, v215, s[58:59] sc0 sc1
	global_store_dword v136, v216, s[58:59] offset:128 sc0 sc1
	s_add_u32 s58, s54, 0xf0000
	s_addc_u32 s59, s55, 0
	global_store_dword v133, v217, s[58:59] sc0 sc1
	global_store_dword v133, v218, s[58:59] offset:128 sc0 sc1
	global_store_dword v134, v219, s[58:59] sc0 sc1
	global_store_dword v134, v220, s[58:59] offset:128 sc0 sc1
	global_store_dword v135, v221, s[58:59] sc0 sc1
	global_store_dword v135, v222, s[58:59] offset:128 sc0 sc1
	global_store_dword v136, v223, s[58:59] sc0 sc1
	global_store_dword v136, v224, s[58:59] offset:128 sc0 sc1
	s_branch .LBB0_1637
